# P5 prologue loop unrolled with 16 loads in flight; P2 early queue ticket; gdn_a<64> KK^T/QK^T tile stage hand-written (fragments read up front, shared B fragment)
# speedup vs baseline: 1.1280x; 1.0082x over previous
_Z4mega1P:
	s_mov_b32 s98, 0
	s_mov_b32 s99, 0
	s_mov_b64 s[80:81], s[0:1]
	v_writelane_b32 v253, s2, 0
	s_load_dwordx8 s[0:7], s[80:81], 0x100
	v_and_b32_e32 v230, 0x3ff, v0
	v_cmp_gt_u32_e32 vcc, 4, v230
	s_waitcnt lgkmcnt(0)
	v_writelane_b32 v253, s0, 1
	s_nop 1
	v_writelane_b32 v253, s1, 2
	v_writelane_b32 v253, s2, 3
	v_writelane_b32 v253, s3, 4
	v_writelane_b32 v253, s4, 5
	v_writelane_b32 v253, s5, 6
	v_writelane_b32 v253, s6, 7
	v_writelane_b32 v253, s7, 8
	s_load_dwordx2 s[96:97], s[80:81], 0x120
	s_load_dwordx4 s[8:11], s[80:81], 0x128
	s_load_dword s0, s[80:81], 0x140
	s_add_u32 s4, s80, 0x138
	s_addc_u32 s5, s81, 0
	s_waitcnt lgkmcnt(0)
	v_writelane_b32 v253, s0, 9
	s_load_dwordx2 s[0:1], s[80:81], 0x138
	s_waitcnt lgkmcnt(0)
	v_writelane_b32 v253, s0, 10
	s_nop 1
	v_writelane_b32 v253, s1, 11
	s_and_saveexec_b64 s[2:3], vcc
	v_lshl_add_u32 v1, v230, 2, 0
	v_add_u32_e32 v1, 0x23fe0, v1
	v_mov_b32_e32 v2, 0
	ds_write_b32 v1, v2
	v_writelane_b32 v253, s8, 12
	s_nop 1
	v_writelane_b32 v253, s9, 13
	v_writelane_b32 v253, s10, 14
	v_writelane_b32 v253, s11, 15
	s_or_b64 exec, exec, s[2:3]
	s_add_u32 s0, s96, 0x2904c100
	s_addc_u32 s1, s97, 0
	v_writelane_b32 v253, s0, 16
	s_waitcnt lgkmcnt(0)
	s_barrier
	v_writelane_b32 v253, s1, 17
	s_getreg_b32 s0, hwreg(HW_REG_XCC_ID, 0, 4)
	s_and_b32 s0, s0, 15
	v_writelane_b32 v253, s0, 18
	v_cmp_eq_u32_e64 s[0:1], 0, v230
	s_mov_b64 s[2:3], exec
	s_nop 0
	v_writelane_b32 v253, s0, 19
	s_nop 1
	v_writelane_b32 v253, s1, 20
	s_and_b64 s[0:1], s[2:3], s[0:1]
	s_mov_b64 exec, s[0:1]
	s_cbranch_execz .LBB0_5
	s_mov_b64 s[6:7], exec
	v_mbcnt_lo_u32_b32 v1, s6, 0
	v_mbcnt_hi_u32_b32 v1, s7, v1
	v_cmp_eq_u32_e32 vcc, 0, v1
	s_and_b64 s[0:1], exec, vcc
	s_mov_b64 exec, s[0:1]
	s_cbranch_execz .LBB0_5
	v_readlane_b32 s0, v253, 18
	s_lshl_b32 s0, s0, 8
	s_bcnt1_i32_b64 s1, s[6:7]
	v_mov_b32_e32 v1, s0
	v_mov_b32_e32 v2, s1
	v_readlane_b32 s0, v253, 16
	v_readlane_b32 s1, v253, 17
	s_nop 4
	global_atomic_add v1, v2, s[0:1] offset:1024

.Lco64_skip:
	s_nop 0
	v_cmp_eq_u32_e32 vcc, 0, v0
	s_and_saveexec_b64 s[0:1], vcc
	s_cbranch_execz .LBB0_748
	s_cmp_eq_u32 s99, 0
	s_cbranch_scc1 .Lpop2_fresh
	s_mov_b32 s99, 0
	s_waitcnt vmcnt(6)
	v_mov_b32_e32 v0, 0
	v_readfirstlane_b32 s4, v252
	s_branch .Lpop2_have
.Lpop2_fresh:
	s_mov_b64 s[38:39], exec
	v_mbcnt_lo_u32_b32 v0, s38, 0
	v_mbcnt_hi_u32_b32 v0, s39, v0
	v_cmp_eq_u32_e32 vcc, 0, v0
	s_and_saveexec_b64 s[36:37], vcc
	s_cbranch_execz .LBB0_747
	s_bcnt1_i32_b64 s4, s[38:39]
	v_mov_b32_e32 v1, s4
	global_atomic_add v1, v105, v1, s[90:91] sc0

.Lpop2_have:
	v_mov_b32_e32 v1, s20
	s_nop 0
	v_add_u32_e32 v0, s4, v0
	ds_write_b32 v1, v0

.LBB0_906:
	s_or_b64 exec, exec, s[0:1]
	s_ashr_i32 s4, s4, 6
	s_cmp_gt_i32 s4, 31
	s_waitcnt lgkmcnt(0)
	s_barrier
	s_cbranch_scc1 .LBB0_933
	s_add_u32 s36, s38, 0xc000
	s_addc_u32 s37, s39, 0
	v_and_b32_e32 v10, 15, v80
	v_and_b32_e32 v11, 48, v80
	v_lshrrev_b32_e32 v12, 2, v80
	v_and_b32_e32 v12, 12, v12
	v_mul_u32_u24_e32 v0, 0x110, v10
	v_add_u32_e32 v0, v0, v11
	s_and_b32 s5, s4, 3
	s_lshr_b32 s6, s4, 2
	s_mul_i32 s7, s5, 0x1100
	s_add_i32 s7, s7, 0x4600
	v_add_u32_e32 v1, s7, v0
	ds_read_b128 v[134:137], v1 offset:0
	ds_read_b128 v[138:141], v1 offset:64
	ds_read_b128 v[142:145], v1 offset:128
	ds_read_b128 v[146:149], v1 offset:192
	s_mul_i32 s0, s6, 0x1100
	s_add_i32 s1, s0, 0x4600
	v_add_u32_e32 v2, s1, v0
	s_add_i32 s1, s0, 0x200
	v_add_u32_e32 v3, s1, v0
	v_lshl_add_u32 v4, s6, 6, v11
	v_lshlrev_b32_e32 v5, 2, v10
	v_lshl_add_u32 v5, s5, 6, v5
	v_lshl_add_u32 v13, s5, 4, v10
	v_lshl_add_u32 v14, s6, 4, v12
	v_lshlrev_b32_e32 v15, 8, v14
	v_lshl_add_u32 v15, v13, 2, v15
	v_add_u32_e32 v15, 0x8a00, v15
	v_lshlrev_b32_e32 v16, 7, v14
	v_lshl_add_u32 v16, v13, 1, v16
	v_mov_b32_e32 v17, 0
	v_lshl_add_u64 v[6:7], s[36:37], 0, v[16:17]
	ds_read_b128 v[150:153], v2 offset:0
	ds_read_b128 v[154:157], v2 offset:64
	ds_read_b128 v[158:161], v2 offset:128
	ds_read_b128 v[162:165], v2 offset:192
	ds_read_b128 v[166:169], v2 offset:8704
	ds_read_b128 v[170:173], v2 offset:8768
	ds_read_b128 v[174:177], v2 offset:8832
	ds_read_b128 v[178:181], v2 offset:8896
	s_waitcnt lgkmcnt(7)
	v_mfma_f32_16x16x32_bf16 v[232:235], v[150:153], v[134:137], 0
	s_waitcnt lgkmcnt(6)
	v_mfma_f32_16x16x32_bf16 v[232:235], v[154:157], v[138:141], v[232:235]
	s_waitcnt lgkmcnt(5)
	v_mfma_f32_16x16x32_bf16 v[232:235], v[158:161], v[142:145], v[232:235]
	s_waitcnt lgkmcnt(4)
	v_mfma_f32_16x16x32_bf16 v[232:235], v[162:165], v[146:149], v[232:235]
	ds_read_b128 v[182:185], v3 offset:0
	ds_read_b128 v[186:189], v3 offset:64
	ds_read_b128 v[190:193], v3 offset:128
	ds_read_b128 v[194:197], v3 offset:192
	s_waitcnt lgkmcnt(7)
	v_mfma_f32_16x16x32_bf16 v[236:239], v[166:169], v[134:137], 0
	s_waitcnt lgkmcnt(6)
	v_mfma_f32_16x16x32_bf16 v[236:239], v[170:173], v[138:141], v[236:239]
	s_waitcnt lgkmcnt(5)
	v_mfma_f32_16x16x32_bf16 v[236:239], v[174:177], v[142:145], v[236:239]
	s_waitcnt lgkmcnt(4)
	v_mfma_f32_16x16x32_bf16 v[236:239], v[178:181], v[146:149], v[236:239]
	ds_read_b128 v[198:201], v3 offset:8704
	ds_read_b128 v[202:205], v3 offset:8768
	ds_read_b128 v[206:209], v3 offset:8832
	ds_read_b128 v[210:213], v3 offset:8896
	ds_read_b128 v[214:217], v4 offset:0
	ds_read_b128 v[222:225], v4 offset:256
	ds_read_b128 v[218:221], v4 offset:128
	ds_read_b128 v[226:229], v4 offset:384
	ds_read_b32 v231, v5
	s_waitcnt lgkmcnt(12)
	v_mfma_f32_16x16x32_bf16 v[240:243], v[182:185], v[134:137], 0
	s_waitcnt lgkmcnt(11)
	v_mfma_f32_16x16x32_bf16 v[240:243], v[186:189], v[138:141], v[240:243]
	s_waitcnt lgkmcnt(10)
	v_mfma_f32_16x16x32_bf16 v[240:243], v[190:193], v[142:145], v[240:243]
	s_waitcnt lgkmcnt(9)
	v_mfma_f32_16x16x32_bf16 v[240:243], v[194:197], v[146:149], v[240:243]
	s_waitcnt lgkmcnt(8)
	v_mfma_f32_16x16x32_bf16 v[244:247], v[198:201], v[134:137], 0
	s_waitcnt lgkmcnt(7)
	v_mfma_f32_16x16x32_bf16 v[244:247], v[202:205], v[138:141], v[244:247]
	s_waitcnt lgkmcnt(6)
	v_mfma_f32_16x16x32_bf16 v[244:247], v[206:209], v[142:145], v[244:247]
	s_waitcnt lgkmcnt(5)
	v_mfma_f32_16x16x32_bf16 v[244:247], v[210:213], v[146:149], v[244:247]
	s_waitcnt lgkmcnt(0)
	v_sub_f32_e32 v214, v214, v231
	v_mul_f32_e32 v214, 0x3fb8aa3b, v214
	v_sub_f32_e32 v215, v215, v231
	v_mul_f32_e32 v215, 0x3fb8aa3b, v215
	v_sub_f32_e32 v216, v216, v231
	v_mul_f32_e32 v216, 0x3fb8aa3b, v216
	v_sub_f32_e32 v217, v217, v231
	v_mul_f32_e32 v217, 0x3fb8aa3b, v217
	v_sub_f32_e32 v218, v218, v231
	v_mul_f32_e32 v218, 0x3fb8aa3b, v218
	v_sub_f32_e32 v219, v219, v231
	v_mul_f32_e32 v219, 0x3fb8aa3b, v219
	v_sub_f32_e32 v220, v220, v231
	v_mul_f32_e32 v220, 0x3fb8aa3b, v220
	v_sub_f32_e32 v221, v221, v231
	v_mul_f32_e32 v221, 0x3fb8aa3b, v221
	v_exp_f32_e32 v214, v214
	v_exp_f32_e32 v215, v215
	v_exp_f32_e32 v216, v216
	v_exp_f32_e32 v217, v217
	v_exp_f32_e32 v218, v218
	v_exp_f32_e32 v219, v219
	v_exp_f32_e32 v220, v220
	v_exp_f32_e32 v221, v221
	s_nop 0
	v_add_u32_e32 v8, 0, v14
	v_mul_f32_e32 v9, v232, v222
	v_mul_f32_e32 v9, v214, v9
	v_cmp_gt_i32_e32 vcc, v8, v13
	s_nop 1
	v_cndmask_b32_e32 v9, 0, v9, vcc
	ds_write_b32 v15, v9 offset:0
	v_add_u32_e32 v8, 1, v14
	v_mul_f32_e32 v9, v233, v223
	v_mul_f32_e32 v9, v215, v9
	v_cmp_gt_i32_e32 vcc, v8, v13
	s_nop 1
	v_cndmask_b32_e32 v9, 0, v9, vcc
	ds_write_b32 v15, v9 offset:256
	v_add_u32_e32 v8, 2, v14
	v_mul_f32_e32 v9, v234, v224
	v_mul_f32_e32 v9, v216, v9
	v_cmp_gt_i32_e32 vcc, v8, v13
	s_nop 1
	v_cndmask_b32_e32 v9, 0, v9, vcc
	ds_write_b32 v15, v9 offset:512
	v_add_u32_e32 v8, 3, v14
	v_mul_f32_e32 v9, v235, v225
	v_mul_f32_e32 v9, v217, v9
	v_cmp_gt_i32_e32 vcc, v8, v13
	s_nop 1
	v_cndmask_b32_e32 v9, 0, v9, vcc
	ds_write_b32 v15, v9 offset:768
	v_add_u32_e32 v8, 32, v14
	v_mul_f32_e32 v9, v236, v226
	v_mul_f32_e32 v9, v218, v9
	v_cmp_gt_i32_e32 vcc, v8, v13
	s_nop 1
	v_cndmask_b32_e32 v9, 0, v9, vcc
	ds_write_b32 v15, v9 offset:8192
	v_add_u32_e32 v8, 33, v14
	v_mul_f32_e32 v9, v237, v227
	v_mul_f32_e32 v9, v219, v9
	v_cmp_gt_i32_e32 vcc, v8, v13
	s_nop 1
	v_cndmask_b32_e32 v9, 0, v9, vcc
	ds_write_b32 v15, v9 offset:8448
	v_add_u32_e32 v8, 34, v14
	v_mul_f32_e32 v9, v238, v228
	v_mul_f32_e32 v9, v220, v9
	v_cmp_gt_i32_e32 vcc, v8, v13
	s_nop 1
	v_cndmask_b32_e32 v9, 0, v9, vcc
	ds_write_b32 v15, v9 offset:8704
	v_add_u32_e32 v8, 35, v14
	v_mul_f32_e32 v9, v239, v229
	v_mul_f32_e32 v9, v221, v9
	v_cmp_gt_i32_e32 vcc, v8, v13
	s_nop 1
	v_cndmask_b32_e32 v9, 0, v9, vcc
	ds_write_b32 v15, v9 offset:8960
	v_add_u32_e32 v8, 0, v14
	v_mul_f32_e32 v9, v240, v214
	v_cvt_pk_bf16_f32 v9, v9, s0
	v_cmp_ge_i32_e32 vcc, v8, v13
	s_nop 1
	v_cndmask_b32_e32 v18, 0, v9, vcc
	global_store_short v[6:7], v18, off offset:0
	v_add_u32_e32 v8, 1, v14
	v_mul_f32_e32 v9, v241, v215
	v_cvt_pk_bf16_f32 v9, v9, s0
	v_cmp_ge_i32_e32 vcc, v8, v13
	s_nop 1
	v_cndmask_b32_e32 v19, 0, v9, vcc
	global_store_short v[6:7], v19, off offset:128
	v_add_u32_e32 v8, 2, v14
	v_mul_f32_e32 v9, v242, v216
	v_cvt_pk_bf16_f32 v9, v9, s0
	v_cmp_ge_i32_e32 vcc, v8, v13
	s_nop 1
	v_cndmask_b32_e32 v18, 0, v9, vcc
	global_store_short v[6:7], v18, off offset:256
	v_add_u32_e32 v8, 3, v14
	v_mul_f32_e32 v9, v243, v217
	v_cvt_pk_bf16_f32 v9, v9, s0
	v_cmp_ge_i32_e32 vcc, v8, v13
	s_nop 1
	v_cndmask_b32_e32 v19, 0, v9, vcc
	global_store_short v[6:7], v19, off offset:384
	v_add_co_u32_e32 v6, vcc, 0x1000, v6
	s_nop 1
	v_addc_co_u32_e32 v7, vcc, 0, v7, vcc
	v_add_u32_e32 v8, 32, v14
	v_mul_f32_e32 v9, v244, v218
	v_cvt_pk_bf16_f32 v9, v9, s0
	v_cmp_ge_i32_e32 vcc, v8, v13
	s_nop 1
	v_cndmask_b32_e32 v18, 0, v9, vcc
	global_store_short v[6:7], v18, off offset:0
	v_add_u32_e32 v8, 33, v14
	v_mul_f32_e32 v9, v245, v219
	v_cvt_pk_bf16_f32 v9, v9, s0
	v_cmp_ge_i32_e32 vcc, v8, v13
	s_nop 1
	v_cndmask_b32_e32 v19, 0, v9, vcc
	global_store_short v[6:7], v19, off offset:128
	v_add_u32_e32 v8, 34, v14
	v_mul_f32_e32 v9, v246, v220
	v_cvt_pk_bf16_f32 v9, v9, s0
	v_cmp_ge_i32_e32 vcc, v8, v13
	s_nop 1
	v_cndmask_b32_e32 v18, 0, v9, vcc
	global_store_short v[6:7], v18, off offset:256
	v_add_u32_e32 v8, 35, v14
	v_mul_f32_e32 v9, v247, v221
	v_cvt_pk_bf16_f32 v9, v9, s0
	v_cmp_ge_i32_e32 vcc, v8, v13
	s_nop 1
	v_cndmask_b32_e32 v19, 0, v9, vcc
	global_store_short v[6:7], v19, off offset:384
.LBB0_933:
	v_cmp_gt_i32_e32 vcc, s27, v80
	s_waitcnt lgkmcnt(0)
	s_barrier
	s_mov_b32 s98, 1
	s_mov_b64 s[100:101], s[38:39]
	v_cmp_eq_u32_e32 vcc, 0, v80
	s_and_saveexec_b64 s[4:5], vcc
	s_cbranch_execz .Lpop2_noissue
	v_mov_b32_e32 v252, 1
	global_atomic_add v252, v105, v252, s[90:91] sc0
	s_mov_b32 s99, 1
.Lpop2_noissue:
	s_or_b64 exec, exec, s[4:5]
	v_cmp_gt_i32_e32 vcc, s27, v80
	s_and_saveexec_b64 s[0:1], vcc
	s_xor_b64 s[0:1], exec, s[0:1]
	s_cbranch_execz .LBB0_939
	v_lshl_add_u32 v1, v80, 2, 0
	v_add_u32_e32 v1, 0xca00, v1
	ds_read_b32 v0, v1 offset:0
	ds_read2st64_b32 v[4:5], v1 offset0:4 offset1:8
	ds_read2st64_b32 v[6:7], v1 offset0:12 offset1:16
	ds_read2st64_b32 v[8:9], v1 offset0:20 offset1:24
	ds_read2st64_b32 v[10:11], v1 offset0:28 offset1:32
	ds_read2st64_b32 v[12:13], v1 offset0:36 offset1:40
	ds_read2st64_b32 v[14:15], v1 offset0:44 offset1:48
	ds_read2st64_b32 v[16:17], v1 offset0:52 offset1:56
	ds_read_b32 v18, v1 offset:15360
	ds_read2st64_b32 v[20:21], v1 offset0:64 offset1:68
	ds_read2st64_b32 v[22:23], v1 offset0:72 offset1:76
	ds_read2st64_b32 v[24:25], v1 offset0:80 offset1:84
	ds_read2st64_b32 v[26:27], v1 offset0:88 offset1:92
	ds_read2st64_b32 v[28:29], v1 offset0:96 offset1:100
	ds_read2st64_b32 v[30:31], v1 offset0:104 offset1:108
	ds_read2st64_b32 v[32:33], v1 offset0:112 offset1:116
	ds_read2st64_b32 v[34:35], v1 offset0:120 offset1:124
	ds_read2st64_b32 v[36:37], v1 offset0:128 offset1:132
	ds_read2st64_b32 v[38:39], v1 offset0:136 offset1:140
	ds_read2st64_b32 v[40:41], v1 offset0:144 offset1:148
	ds_read2st64_b32 v[42:43], v1 offset0:152 offset1:156
	ds_read2st64_b32 v[44:45], v1 offset0:160 offset1:164
	ds_read2st64_b32 v[46:47], v1 offset0:168 offset1:172
	ds_read2st64_b32 v[48:49], v1 offset0:176 offset1:180
	ds_read2st64_b32 v[50:51], v1 offset0:184 offset1:188
	ds_read2st64_b32 v[52:53], v1 offset0:192 offset1:196
	ds_read2st64_b32 v[54:55], v1 offset0:200 offset1:204
	ds_read2st64_b32 v[56:57], v1 offset0:208 offset1:212
	ds_read2st64_b32 v[58:59], v1 offset0:216 offset1:220
	ds_read2st64_b32 v[60:61], v1 offset0:224 offset1:228
	ds_read2st64_b32 v[62:63], v1 offset0:232 offset1:236
	ds_read2st64_b32 v[64:65], v1 offset0:240 offset1:244
	ds_read2st64_b32 v[2:3], v1 offset0:248 offset1:252
	ds_read_b128 v[136:139], v105 offset:35584
	ds_read_b128 v[140:143], v105 offset:35840
	ds_read_b128 v[144:147], v105 offset:36096
	ds_read_b128 v[148:151], v105 offset:36352
	ds_read_b128 v[152:155], v105 offset:36608
	ds_read_b128 v[156:159], v105 offset:36624
	ds_read_b128 v[160:163], v105 offset:36864
	ds_read_b128 v[164:167], v105 offset:36880
	ds_read_b128 v[168:171], v105 offset:37120
	ds_read_b128 v[172:175], v105 offset:37136
	ds_read_b128 v[176:179], v105 offset:37376
	ds_read_b128 v[180:183], v105 offset:37392
	s_waitcnt lgkmcnt(11)
	v_mul_f32_e32 v66, v136, v0
	v_sub_f32_e32 v4, v4, v66
	ds_read_b128 v[136:139], v105 offset:37632
	s_waitcnt lgkmcnt(11)
	v_mul_f32_e32 v66, v140, v0
	v_mul_f32_e32 v67, v141, v4
	v_sub_f32_e32 v5, v5, v66
	v_sub_f32_e32 v5, v5, v67
	ds_read_b128 v[140:143], v105 offset:37648
	s_waitcnt lgkmcnt(11)
	v_mul_f32_e32 v66, v144, v0
	v_mul_f32_e32 v67, v145, v4
	v_fmac_f32_e32 v66, v146, v5
	v_sub_f32_e32 v6, v6, v66
	v_sub_f32_e32 v6, v6, v67
	ds_read_b128 v[144:147], v105 offset:37664
	s_waitcnt lgkmcnt(11)
	v_mul_f32_e32 v66, v148, v0
	v_mul_f32_e32 v67, v149, v4
	v_fmac_f32_e32 v66, v150, v5
	v_fmac_f32_e32 v67, v151, v6
	v_sub_f32_e32 v7, v7, v66
	v_sub_f32_e32 v7, v7, v67
	ds_read_b128 v[148:151], v105 offset:37888
	s_waitcnt lgkmcnt(11)
	v_mul_f32_e32 v66, v152, v0
	v_mul_f32_e32 v67, v153, v4
	v_fmac_f32_e32 v66, v154, v5
	v_fmac_f32_e32 v67, v155, v6
	ds_read_b128 v[152:155], v105 offset:37904
	s_waitcnt lgkmcnt(11)
	v_fmac_f32_e32 v66, v156, v7
	v_sub_f32_e32 v8, v8, v66
	v_sub_f32_e32 v8, v8, v67
	ds_read_b128 v[156:159], v105 offset:37920
	s_waitcnt lgkmcnt(11)
	v_mul_f32_e32 v66, v160, v0
	v_mul_f32_e32 v67, v161, v4
	v_fmac_f32_e32 v66, v162, v5
	v_fmac_f32_e32 v67, v163, v6
	ds_read_b128 v[160:163], v105 offset:38144
	s_waitcnt lgkmcnt(11)
	v_fmac_f32_e32 v66, v164, v7
	v_fmac_f32_e32 v67, v165, v8
	v_sub_f32_e32 v9, v9, v66
	v_sub_f32_e32 v9, v9, v67
	ds_read_b128 v[164:167], v105 offset:38160
	s_waitcnt lgkmcnt(11)
	v_mul_f32_e32 v66, v168, v0
	v_mul_f32_e32 v67, v169, v4
	v_fmac_f32_e32 v66, v170, v5
	v_fmac_f32_e32 v67, v171, v6
	ds_read_b128 v[168:171], v105 offset:38176
	s_waitcnt lgkmcnt(11)
	v_fmac_f32_e32 v66, v172, v7
	v_fmac_f32_e32 v67, v173, v8
	v_fmac_f32_e32 v66, v174, v9
	v_sub_f32_e32 v10, v10, v66
	v_sub_f32_e32 v10, v10, v67
	ds_read_b128 v[172:175], v105 offset:38400
	s_waitcnt lgkmcnt(11)
	v_mul_f32_e32 v66, v176, v0
	v_mul_f32_e32 v67, v177, v4
	v_fmac_f32_e32 v66, v178, v5
	v_fmac_f32_e32 v67, v179, v6
	ds_read_b128 v[176:179], v105 offset:38416
	s_waitcnt lgkmcnt(11)
	v_fmac_f32_e32 v66, v180, v7
	v_fmac_f32_e32 v67, v181, v8
	v_fmac_f32_e32 v66, v182, v9
	v_fmac_f32_e32 v67, v183, v10
	v_sub_f32_e32 v11, v11, v66
	v_sub_f32_e32 v11, v11, v67
	ds_read_b128 v[180:183], v105 offset:38432
	s_waitcnt lgkmcnt(11)
	v_mul_f32_e32 v66, v136, v0
	v_mul_f32_e32 v67, v137, v4
	v_fmac_f32_e32 v66, v138, v5
	v_fmac_f32_e32 v67, v139, v6
	ds_read_b128 v[136:139], v105 offset:38656
	s_waitcnt lgkmcnt(11)
	v_fmac_f32_e32 v66, v140, v7
	v_fmac_f32_e32 v67, v141, v8
	v_fmac_f32_e32 v66, v142, v9
	v_fmac_f32_e32 v67, v143, v10
	ds_read_b128 v[140:143], v105 offset:38672
	s_waitcnt lgkmcnt(11)
	v_fmac_f32_e32 v66, v144, v11
	v_sub_f32_e32 v12, v12, v66
	v_sub_f32_e32 v12, v12, v67
	ds_read_b128 v[144:147], v105 offset:38688
	s_waitcnt lgkmcnt(11)
	v_mul_f32_e32 v66, v148, v0
	v_mul_f32_e32 v67, v149, v4
	v_fmac_f32_e32 v66, v150, v5
	v_fmac_f32_e32 v67, v151, v6
	ds_read_b128 v[148:151], v105 offset:38704
	s_waitcnt lgkmcnt(11)
	v_fmac_f32_e32 v66, v152, v7
	v_fmac_f32_e32 v67, v153, v8
	v_fmac_f32_e32 v66, v154, v9
	v_fmac_f32_e32 v67, v155, v10
	ds_read_b128 v[152:155], v105 offset:38912
	s_waitcnt lgkmcnt(11)
	v_fmac_f32_e32 v66, v156, v11
	v_fmac_f32_e32 v67, v157, v12
	v_sub_f32_e32 v13, v13, v66
	v_sub_f32_e32 v13, v13, v67
	ds_read_b128 v[156:159], v105 offset:38928
	s_waitcnt lgkmcnt(11)
	v_mul_f32_e32 v66, v160, v0
	v_mul_f32_e32 v67, v161, v4
	v_fmac_f32_e32 v66, v162, v5
	v_fmac_f32_e32 v67, v163, v6
	ds_read_b128 v[160:163], v105 offset:38944
	s_waitcnt lgkmcnt(11)
	v_fmac_f32_e32 v66, v164, v7
	v_fmac_f32_e32 v67, v165, v8
	v_fmac_f32_e32 v66, v166, v9
	v_fmac_f32_e32 v67, v167, v10
	ds_read_b128 v[164:167], v105 offset:38960
	s_waitcnt lgkmcnt(11)
	v_fmac_f32_e32 v66, v168, v11
	v_fmac_f32_e32 v67, v169, v12
	v_fmac_f32_e32 v66, v170, v13
	v_sub_f32_e32 v14, v14, v66
	v_sub_f32_e32 v14, v14, v67
	ds_read_b128 v[168:171], v105 offset:39168
	s_waitcnt lgkmcnt(11)
	v_mul_f32_e32 v66, v172, v0
	v_mul_f32_e32 v67, v173, v4
	v_fmac_f32_e32 v66, v174, v5
	v_fmac_f32_e32 v67, v175, v6
	ds_read_b128 v[172:175], v105 offset:39184
	s_waitcnt lgkmcnt(11)
	v_fmac_f32_e32 v66, v176, v7
	v_fmac_f32_e32 v67, v177, v8
	v_fmac_f32_e32 v66, v178, v9
	v_fmac_f32_e32 v67, v179, v10
	ds_read_b128 v[176:179], v105 offset:39200
	s_waitcnt lgkmcnt(11)
	v_fmac_f32_e32 v66, v180, v11
	v_fmac_f32_e32 v67, v181, v12
	v_fmac_f32_e32 v66, v182, v13
	v_fmac_f32_e32 v67, v183, v14
	v_sub_f32_e32 v15, v15, v66
	v_sub_f32_e32 v15, v15, v67
	ds_read_b128 v[180:183], v105 offset:39216
	s_waitcnt lgkmcnt(11)
	v_mul_f32_e32 v66, v136, v0
	v_mul_f32_e32 v67, v137, v4
	v_fmac_f32_e32 v66, v138, v5
	v_fmac_f32_e32 v67, v139, v6
	ds_read_b128 v[136:139], v105 offset:39424
	s_waitcnt lgkmcnt(11)
	v_fmac_f32_e32 v66, v140, v7
	v_fmac_f32_e32 v67, v141, v8
	v_fmac_f32_e32 v66, v142, v9
	v_fmac_f32_e32 v67, v143, v10
	ds_read_b128 v[140:143], v105 offset:39440
	s_waitcnt lgkmcnt(11)
	v_fmac_f32_e32 v66, v144, v11
	v_fmac_f32_e32 v67, v145, v12
	v_fmac_f32_e32 v66, v146, v13
	v_fmac_f32_e32 v67, v147, v14
	ds_read_b128 v[144:147], v105 offset:39456
	s_waitcnt lgkmcnt(11)
	v_fmac_f32_e32 v66, v148, v15
	v_sub_f32_e32 v16, v16, v66
	v_sub_f32_e32 v16, v16, v67
	ds_read_b128 v[148:151], v105 offset:39472
	s_waitcnt lgkmcnt(11)
	v_mul_f32_e32 v66, v152, v0
	v_mul_f32_e32 v67, v153, v4
	v_fmac_f32_e32 v66, v154, v5
	v_fmac_f32_e32 v67, v155, v6
	ds_read_b128 v[152:155], v105 offset:39680
	s_waitcnt lgkmcnt(11)
	v_fmac_f32_e32 v66, v156, v7
	v_fmac_f32_e32 v67, v157, v8
	v_fmac_f32_e32 v66, v158, v9
	v_fmac_f32_e32 v67, v159, v10
	ds_read_b128 v[156:159], v105 offset:39696
	s_waitcnt lgkmcnt(11)
	v_fmac_f32_e32 v66, v160, v11
	v_fmac_f32_e32 v67, v161, v12
	v_fmac_f32_e32 v66, v162, v13
	v_fmac_f32_e32 v67, v163, v14
	ds_read_b128 v[160:163], v105 offset:39712
	s_waitcnt lgkmcnt(11)
	v_fmac_f32_e32 v66, v164, v15
	v_fmac_f32_e32 v67, v165, v16
	v_sub_f32_e32 v17, v17, v66
	v_sub_f32_e32 v17, v17, v67
	ds_read_b128 v[164:167], v105 offset:39728
	s_waitcnt lgkmcnt(11)
	v_mul_f32_e32 v66, v168, v0
	v_mul_f32_e32 v67, v169, v4
	v_fmac_f32_e32 v66, v170, v5
	v_fmac_f32_e32 v67, v171, v6
	ds_read_b128 v[168:171], v105 offset:39744
	s_waitcnt lgkmcnt(11)
	v_fmac_f32_e32 v66, v172, v7
	v_fmac_f32_e32 v67, v173, v8
	v_fmac_f32_e32 v66, v174, v9
	v_fmac_f32_e32 v67, v175, v10
	ds_read_b128 v[172:175], v105 offset:39936
	s_waitcnt lgkmcnt(11)
	v_fmac_f32_e32 v66, v176, v11
	v_fmac_f32_e32 v67, v177, v12
	v_fmac_f32_e32 v66, v178, v13
	v_fmac_f32_e32 v67, v179, v14
	ds_read_b128 v[176:179], v105 offset:39952
	s_waitcnt lgkmcnt(11)
	v_fmac_f32_e32 v66, v180, v15
	v_fmac_f32_e32 v67, v181, v16
	v_fmac_f32_e32 v66, v182, v17
	v_sub_f32_e32 v18, v18, v66
	v_sub_f32_e32 v18, v18, v67
	ds_read_b128 v[180:183], v105 offset:39968
	s_waitcnt lgkmcnt(11)
	v_mul_f32_e32 v66, v136, v0
	v_mul_f32_e32 v67, v137, v4
	v_fmac_f32_e32 v66, v138, v5
	v_fmac_f32_e32 v67, v139, v6
	ds_read_b128 v[136:139], v105 offset:39984
	s_waitcnt lgkmcnt(11)
	v_fmac_f32_e32 v66, v140, v7
	v_fmac_f32_e32 v67, v141, v8
	v_fmac_f32_e32 v66, v142, v9
	v_fmac_f32_e32 v67, v143, v10
	ds_read_b128 v[140:143], v105 offset:40000
	s_waitcnt lgkmcnt(11)
	v_fmac_f32_e32 v66, v144, v11
	v_fmac_f32_e32 v67, v145, v12
	v_fmac_f32_e32 v66, v146, v13
	v_fmac_f32_e32 v67, v147, v14
	ds_read_b128 v[144:147], v105 offset:40192
	s_waitcnt lgkmcnt(11)
	v_fmac_f32_e32 v66, v148, v15
	v_fmac_f32_e32 v67, v149, v16
	v_fmac_f32_e32 v66, v150, v17
	v_fmac_f32_e32 v67, v151, v18
	v_sub_f32_e32 v20, v20, v66
	v_sub_f32_e32 v20, v20, v67
	ds_read_b128 v[148:151], v105 offset:40208
	s_waitcnt lgkmcnt(11)
	v_mul_f32_e32 v66, v152, v0
	v_mul_f32_e32 v67, v153, v4
	v_fmac_f32_e32 v66, v154, v5
	v_fmac_f32_e32 v67, v155, v6
	ds_read_b128 v[152:155], v105 offset:40224
	s_waitcnt lgkmcnt(11)
	v_fmac_f32_e32 v66, v156, v7
	v_fmac_f32_e32 v67, v157, v8
	v_fmac_f32_e32 v66, v158, v9
	v_fmac_f32_e32 v67, v159, v10
	ds_read_b128 v[156:159], v105 offset:40240
	s_waitcnt lgkmcnt(11)
	v_fmac_f32_e32 v66, v160, v11
	v_fmac_f32_e32 v67, v161, v12
	v_fmac_f32_e32 v66, v162, v13
	v_fmac_f32_e32 v67, v163, v14
	ds_read_b128 v[160:163], v105 offset:40256
	s_waitcnt lgkmcnt(11)
	v_fmac_f32_e32 v66, v164, v15
	v_fmac_f32_e32 v67, v165, v16
	v_fmac_f32_e32 v66, v166, v17
	v_fmac_f32_e32 v67, v167, v18
	ds_read_b128 v[164:167], v105 offset:40448
	s_waitcnt lgkmcnt(11)
	v_fmac_f32_e32 v66, v168, v20
	v_sub_f32_e32 v21, v21, v66
	v_sub_f32_e32 v21, v21, v67
	ds_read_b128 v[168:171], v105 offset:40464
	s_waitcnt lgkmcnt(11)
	v_mul_f32_e32 v66, v172, v0
	v_mul_f32_e32 v67, v173, v4
	v_fmac_f32_e32 v66, v174, v5
	v_fmac_f32_e32 v67, v175, v6
	ds_read_b128 v[172:175], v105 offset:40480
	s_waitcnt lgkmcnt(11)
	v_fmac_f32_e32 v66, v176, v7
	v_fmac_f32_e32 v67, v177, v8
	v_fmac_f32_e32 v66, v178, v9
	v_fmac_f32_e32 v67, v179, v10
	ds_read_b128 v[176:179], v105 offset:40496
	s_waitcnt lgkmcnt(11)
	v_fmac_f32_e32 v66, v180, v11
	v_fmac_f32_e32 v67, v181, v12
	v_fmac_f32_e32 v66, v182, v13
	v_fmac_f32_e32 v67, v183, v14
	ds_read_b128 v[180:183], v105 offset:40512
	s_waitcnt lgkmcnt(11)
	v_fmac_f32_e32 v66, v136, v15
	v_fmac_f32_e32 v67, v137, v16
	v_fmac_f32_e32 v66, v138, v17
	v_fmac_f32_e32 v67, v139, v18
	ds_read_b128 v[136:139], v105 offset:40704
	s_waitcnt lgkmcnt(11)
	v_fmac_f32_e32 v66, v140, v20
	v_fmac_f32_e32 v67, v141, v21
	v_sub_f32_e32 v22, v22, v66
	v_sub_f32_e32 v22, v22, v67
	ds_read_b128 v[140:143], v105 offset:40720
	s_waitcnt lgkmcnt(11)
	v_mul_f32_e32 v66, v144, v0
	v_mul_f32_e32 v67, v145, v4
	v_fmac_f32_e32 v66, v146, v5
	v_fmac_f32_e32 v67, v147, v6
	ds_read_b128 v[144:147], v105 offset:40736
	s_waitcnt lgkmcnt(11)
	v_fmac_f32_e32 v66, v148, v7
	v_fmac_f32_e32 v67, v149, v8
	v_fmac_f32_e32 v66, v150, v9
	v_fmac_f32_e32 v67, v151, v10
	ds_read_b128 v[148:151], v105 offset:40752
	s_waitcnt lgkmcnt(11)
	v_fmac_f32_e32 v66, v152, v11
	v_fmac_f32_e32 v67, v153, v12
	v_fmac_f32_e32 v66, v154, v13
	v_fmac_f32_e32 v67, v155, v14
	ds_read_b128 v[152:155], v105 offset:40768
	s_waitcnt lgkmcnt(11)
	v_fmac_f32_e32 v66, v156, v15
	v_fmac_f32_e32 v67, v157, v16
	v_fmac_f32_e32 v66, v158, v17
	v_fmac_f32_e32 v67, v159, v18
	ds_read_b128 v[156:159], v105 offset:40784
	s_waitcnt lgkmcnt(11)
	v_fmac_f32_e32 v66, v160, v20
	v_fmac_f32_e32 v67, v161, v21
	v_fmac_f32_e32 v66, v162, v22
	v_sub_f32_e32 v23, v23, v66
	v_sub_f32_e32 v23, v23, v67
	ds_read_b128 v[160:163], v105 offset:40960
	s_waitcnt lgkmcnt(11)
	v_mul_f32_e32 v66, v164, v0
	v_mul_f32_e32 v67, v165, v4
	v_fmac_f32_e32 v66, v166, v5
	v_fmac_f32_e32 v67, v167, v6
	ds_read_b128 v[164:167], v105 offset:40976
	s_waitcnt lgkmcnt(11)
	v_fmac_f32_e32 v66, v168, v7
	v_fmac_f32_e32 v67, v169, v8
	v_fmac_f32_e32 v66, v170, v9
	v_fmac_f32_e32 v67, v171, v10
	ds_read_b128 v[168:171], v105 offset:40992
	s_waitcnt lgkmcnt(11)
	v_fmac_f32_e32 v66, v172, v11
	v_fmac_f32_e32 v67, v173, v12
	v_fmac_f32_e32 v66, v174, v13
	v_fmac_f32_e32 v67, v175, v14
	ds_read_b128 v[172:175], v105 offset:41008
	s_waitcnt lgkmcnt(11)
	v_fmac_f32_e32 v66, v176, v15
	v_fmac_f32_e32 v67, v177, v16
	v_fmac_f32_e32 v66, v178, v17
	v_fmac_f32_e32 v67, v179, v18
	ds_read_b128 v[176:179], v105 offset:41024
	s_waitcnt lgkmcnt(11)
	v_fmac_f32_e32 v66, v180, v20
	v_fmac_f32_e32 v67, v181, v21
	v_fmac_f32_e32 v66, v182, v22
	v_fmac_f32_e32 v67, v183, v23
	v_sub_f32_e32 v24, v24, v66
	v_sub_f32_e32 v24, v24, v67
	ds_read_b128 v[180:183], v105 offset:41040
	s_waitcnt lgkmcnt(11)
	v_mul_f32_e32 v66, v136, v0
	v_mul_f32_e32 v67, v137, v4
	v_fmac_f32_e32 v66, v138, v5
	v_fmac_f32_e32 v67, v139, v6
	ds_read_b128 v[136:139], v105 offset:41216
	s_waitcnt lgkmcnt(11)
	v_fmac_f32_e32 v66, v140, v7
	v_fmac_f32_e32 v67, v141, v8
	v_fmac_f32_e32 v66, v142, v9
	v_fmac_f32_e32 v67, v143, v10
	ds_read_b128 v[140:143], v105 offset:41232
	s_waitcnt lgkmcnt(11)
	v_fmac_f32_e32 v66, v144, v11
	v_fmac_f32_e32 v67, v145, v12
	v_fmac_f32_e32 v66, v146, v13
	v_fmac_f32_e32 v67, v147, v14
	ds_read_b128 v[144:147], v105 offset:41248
	s_waitcnt lgkmcnt(11)
	v_fmac_f32_e32 v66, v148, v15
	v_fmac_f32_e32 v67, v149, v16
	v_fmac_f32_e32 v66, v150, v17
	v_fmac_f32_e32 v67, v151, v18
	ds_read_b128 v[148:151], v105 offset:41264
	s_waitcnt lgkmcnt(11)
	v_fmac_f32_e32 v66, v152, v20
	v_fmac_f32_e32 v67, v153, v21
	v_fmac_f32_e32 v66, v154, v22
	v_fmac_f32_e32 v67, v155, v23
	ds_read_b128 v[152:155], v105 offset:41280
	s_waitcnt lgkmcnt(11)
	v_fmac_f32_e32 v66, v156, v24
	v_sub_f32_e32 v25, v25, v66
	v_sub_f32_e32 v25, v25, v67
	ds_read_b128 v[156:159], v105 offset:41296
	s_waitcnt lgkmcnt(11)
	v_mul_f32_e32 v66, v160, v0
	v_mul_f32_e32 v67, v161, v4
	v_fmac_f32_e32 v66, v162, v5
	v_fmac_f32_e32 v67, v163, v6
	ds_read_b128 v[160:163], v105 offset:41472
	s_waitcnt lgkmcnt(11)
	v_fmac_f32_e32 v66, v164, v7
	v_fmac_f32_e32 v67, v165, v8
	v_fmac_f32_e32 v66, v166, v9
	v_fmac_f32_e32 v67, v167, v10
	ds_read_b128 v[164:167], v105 offset:41488
	s_waitcnt lgkmcnt(11)
	v_fmac_f32_e32 v66, v168, v11
	v_fmac_f32_e32 v67, v169, v12
	v_fmac_f32_e32 v66, v170, v13
	v_fmac_f32_e32 v67, v171, v14
	ds_read_b128 v[168:171], v105 offset:41504
	s_waitcnt lgkmcnt(11)
	v_fmac_f32_e32 v66, v172, v15
	v_fmac_f32_e32 v67, v173, v16
	v_fmac_f32_e32 v66, v174, v17
	v_fmac_f32_e32 v67, v175, v18
	ds_read_b128 v[172:175], v105 offset:41520
	s_waitcnt lgkmcnt(11)
	v_fmac_f32_e32 v66, v176, v20
	v_fmac_f32_e32 v67, v177, v21
	v_fmac_f32_e32 v66, v178, v22
	v_fmac_f32_e32 v67, v179, v23
	ds_read_b128 v[176:179], v105 offset:41536
	s_waitcnt lgkmcnt(11)
	v_fmac_f32_e32 v66, v180, v24
	v_fmac_f32_e32 v67, v181, v25
	v_sub_f32_e32 v26, v26, v66
	v_sub_f32_e32 v26, v26, v67
	ds_read_b128 v[180:183], v105 offset:41552
	s_waitcnt lgkmcnt(11)
	v_mul_f32_e32 v66, v136, v0
	v_mul_f32_e32 v67, v137, v4
	v_fmac_f32_e32 v66, v138, v5
	v_fmac_f32_e32 v67, v139, v6
	ds_read_b128 v[136:139], v105 offset:41728
	s_waitcnt lgkmcnt(11)
	v_fmac_f32_e32 v66, v140, v7
	v_fmac_f32_e32 v67, v141, v8
	v_fmac_f32_e32 v66, v142, v9
	v_fmac_f32_e32 v67, v143, v10
	ds_read_b128 v[140:143], v105 offset:41744
	s_waitcnt lgkmcnt(11)
	v_fmac_f32_e32 v66, v144, v11
	v_fmac_f32_e32 v67, v145, v12
	v_fmac_f32_e32 v66, v146, v13
	v_fmac_f32_e32 v67, v147, v14
	ds_read_b128 v[144:147], v105 offset:41760
	s_waitcnt lgkmcnt(11)
	v_fmac_f32_e32 v66, v148, v15
	v_fmac_f32_e32 v67, v149, v16
	v_fmac_f32_e32 v66, v150, v17
	v_fmac_f32_e32 v67, v151, v18
	ds_read_b128 v[148:151], v105 offset:41776
	s_waitcnt lgkmcnt(11)
	v_fmac_f32_e32 v66, v152, v20
	v_fmac_f32_e32 v67, v153, v21
	v_fmac_f32_e32 v66, v154, v22
	v_fmac_f32_e32 v67, v155, v23
	ds_read_b128 v[152:155], v105 offset:41792
	s_waitcnt lgkmcnt(11)
	v_fmac_f32_e32 v66, v156, v24
	v_fmac_f32_e32 v67, v157, v25
	v_fmac_f32_e32 v66, v158, v26
	v_sub_f32_e32 v27, v27, v66
	v_sub_f32_e32 v27, v27, v67
	ds_read_b128 v[156:159], v105 offset:41808
	s_waitcnt lgkmcnt(11)
	v_mul_f32_e32 v66, v160, v0
	v_mul_f32_e32 v67, v161, v4
	v_fmac_f32_e32 v66, v162, v5
	v_fmac_f32_e32 v67, v163, v6
	ds_read_b128 v[160:163], v105 offset:41824
	s_waitcnt lgkmcnt(11)
	v_fmac_f32_e32 v66, v164, v7
	v_fmac_f32_e32 v67, v165, v8
	v_fmac_f32_e32 v66, v166, v9
	v_fmac_f32_e32 v67, v167, v10
	ds_read_b128 v[164:167], v105 offset:41984
	s_waitcnt lgkmcnt(11)
	v_fmac_f32_e32 v66, v168, v11
	v_fmac_f32_e32 v67, v169, v12
	v_fmac_f32_e32 v66, v170, v13
	v_fmac_f32_e32 v67, v171, v14
	ds_read_b128 v[168:171], v105 offset:42000
	s_waitcnt lgkmcnt(11)
	v_fmac_f32_e32 v66, v172, v15
	v_fmac_f32_e32 v67, v173, v16
	v_fmac_f32_e32 v66, v174, v17
	v_fmac_f32_e32 v67, v175, v18
	ds_read_b128 v[172:175], v105 offset:42016
	s_waitcnt lgkmcnt(11)
	v_fmac_f32_e32 v66, v176, v20
	v_fmac_f32_e32 v67, v177, v21
	v_fmac_f32_e32 v66, v178, v22
	v_fmac_f32_e32 v67, v179, v23
	ds_read_b128 v[176:179], v105 offset:42032
	s_waitcnt lgkmcnt(11)
	v_fmac_f32_e32 v66, v180, v24
	v_fmac_f32_e32 v67, v181, v25
	v_fmac_f32_e32 v66, v182, v26
	v_fmac_f32_e32 v67, v183, v27
	v_sub_f32_e32 v28, v28, v66
	v_sub_f32_e32 v28, v28, v67
	ds_read_b128 v[180:183], v105 offset:42048
	s_waitcnt lgkmcnt(11)
	v_mul_f32_e32 v66, v136, v0
	v_mul_f32_e32 v67, v137, v4
	v_fmac_f32_e32 v66, v138, v5
	v_fmac_f32_e32 v67, v139, v6
	ds_read_b128 v[136:139], v105 offset:42064
	s_waitcnt lgkmcnt(11)
	v_fmac_f32_e32 v66, v140, v7
	v_fmac_f32_e32 v67, v141, v8
	v_fmac_f32_e32 v66, v142, v9
	v_fmac_f32_e32 v67, v143, v10
	ds_read_b128 v[140:143], v105 offset:42080
	s_waitcnt lgkmcnt(11)
	v_fmac_f32_e32 v66, v144, v11
	v_fmac_f32_e32 v67, v145, v12
	v_fmac_f32_e32 v66, v146, v13
	v_fmac_f32_e32 v67, v147, v14
	ds_read_b128 v[144:147], v105 offset:42240
	s_waitcnt lgkmcnt(11)
	v_fmac_f32_e32 v66, v148, v15
	v_fmac_f32_e32 v67, v149, v16
	v_fmac_f32_e32 v66, v150, v17
	v_fmac_f32_e32 v67, v151, v18
	ds_read_b128 v[148:151], v105 offset:42256
	s_waitcnt lgkmcnt(11)
	v_fmac_f32_e32 v66, v152, v20
	v_fmac_f32_e32 v67, v153, v21
	v_fmac_f32_e32 v66, v154, v22
	v_fmac_f32_e32 v67, v155, v23
	ds_read_b128 v[152:155], v105 offset:42272
	s_waitcnt lgkmcnt(11)
	v_fmac_f32_e32 v66, v156, v24
	v_fmac_f32_e32 v67, v157, v25
	v_fmac_f32_e32 v66, v158, v26
	v_fmac_f32_e32 v67, v159, v27
	ds_read_b128 v[156:159], v105 offset:42288
	s_waitcnt lgkmcnt(11)
	v_fmac_f32_e32 v66, v160, v28
	v_sub_f32_e32 v29, v29, v66
	v_sub_f32_e32 v29, v29, v67
	ds_read_b128 v[160:163], v105 offset:42304
	s_waitcnt lgkmcnt(11)
	v_mul_f32_e32 v66, v164, v0
	v_mul_f32_e32 v67, v165, v4
	v_fmac_f32_e32 v66, v166, v5
	v_fmac_f32_e32 v67, v167, v6
	ds_read_b128 v[164:167], v105 offset:42320
	s_waitcnt lgkmcnt(11)
	v_fmac_f32_e32 v66, v168, v7
	v_fmac_f32_e32 v67, v169, v8
	v_fmac_f32_e32 v66, v170, v9
	v_fmac_f32_e32 v67, v171, v10
	ds_read_b128 v[168:171], v105 offset:42336
	s_waitcnt lgkmcnt(11)
	v_fmac_f32_e32 v66, v172, v11
	v_fmac_f32_e32 v67, v173, v12
	v_fmac_f32_e32 v66, v174, v13
	v_fmac_f32_e32 v67, v175, v14
	ds_read_b128 v[172:175], v105 offset:42496
	s_waitcnt lgkmcnt(11)
	v_fmac_f32_e32 v66, v176, v15
	v_fmac_f32_e32 v67, v177, v16
	v_fmac_f32_e32 v66, v178, v17
	v_fmac_f32_e32 v67, v179, v18
	ds_read_b128 v[176:179], v105 offset:42512
	s_waitcnt lgkmcnt(11)
	v_fmac_f32_e32 v66, v180, v20
	v_fmac_f32_e32 v67, v181, v21
	v_fmac_f32_e32 v66, v182, v22
	v_fmac_f32_e32 v67, v183, v23
	ds_read_b128 v[180:183], v105 offset:42528
	s_waitcnt lgkmcnt(11)
	v_fmac_f32_e32 v66, v136, v24
	v_fmac_f32_e32 v67, v137, v25
	v_fmac_f32_e32 v66, v138, v26
	v_fmac_f32_e32 v67, v139, v27
	ds_read_b128 v[136:139], v105 offset:42544
	s_waitcnt lgkmcnt(11)
	v_fmac_f32_e32 v66, v140, v28
	v_fmac_f32_e32 v67, v141, v29
	v_sub_f32_e32 v30, v30, v66
	v_sub_f32_e32 v30, v30, v67
	ds_read_b128 v[140:143], v105 offset:42560
	s_waitcnt lgkmcnt(11)
	v_mul_f32_e32 v66, v144, v0
	v_mul_f32_e32 v67, v145, v4
	v_fmac_f32_e32 v66, v146, v5
	v_fmac_f32_e32 v67, v147, v6
	ds_read_b128 v[144:147], v105 offset:42576
	s_waitcnt lgkmcnt(11)
	v_fmac_f32_e32 v66, v148, v7
	v_fmac_f32_e32 v67, v149, v8
	v_fmac_f32_e32 v66, v150, v9
	v_fmac_f32_e32 v67, v151, v10
	ds_read_b128 v[148:151], v105 offset:42592
	s_waitcnt lgkmcnt(11)
	v_fmac_f32_e32 v66, v152, v11
	v_fmac_f32_e32 v67, v153, v12
	v_fmac_f32_e32 v66, v154, v13
	v_fmac_f32_e32 v67, v155, v14
	ds_read_b128 v[152:155], v105 offset:42752
	s_waitcnt lgkmcnt(11)
	v_fmac_f32_e32 v66, v156, v15
	v_fmac_f32_e32 v67, v157, v16
	v_fmac_f32_e32 v66, v158, v17
	v_fmac_f32_e32 v67, v159, v18
	ds_read_b128 v[156:159], v105 offset:42768
	s_waitcnt lgkmcnt(11)
	v_fmac_f32_e32 v66, v160, v20
	v_fmac_f32_e32 v67, v161, v21
	v_fmac_f32_e32 v66, v162, v22
	v_fmac_f32_e32 v67, v163, v23
	ds_read_b128 v[160:163], v105 offset:42784
	s_waitcnt lgkmcnt(11)
	v_fmac_f32_e32 v66, v164, v24
	v_fmac_f32_e32 v67, v165, v25
	v_fmac_f32_e32 v66, v166, v26
	v_fmac_f32_e32 v67, v167, v27
	ds_read_b128 v[164:167], v105 offset:42800
	s_waitcnt lgkmcnt(11)
	v_fmac_f32_e32 v66, v168, v28
	v_fmac_f32_e32 v67, v169, v29
	v_fmac_f32_e32 v66, v170, v30
	v_sub_f32_e32 v31, v31, v66
	v_sub_f32_e32 v31, v31, v67
	ds_read_b128 v[168:171], v105 offset:42816
	s_waitcnt lgkmcnt(11)
	v_mul_f32_e32 v66, v172, v0
	v_mul_f32_e32 v67, v173, v4
	v_fmac_f32_e32 v66, v174, v5
	v_fmac_f32_e32 v67, v175, v6
	ds_read_b128 v[172:175], v105 offset:42832
	s_waitcnt lgkmcnt(11)
	v_fmac_f32_e32 v66, v176, v7
	v_fmac_f32_e32 v67, v177, v8
	v_fmac_f32_e32 v66, v178, v9
	v_fmac_f32_e32 v67, v179, v10
	ds_read_b128 v[176:179], v105 offset:42848
	s_waitcnt lgkmcnt(11)
	v_fmac_f32_e32 v66, v180, v11
	v_fmac_f32_e32 v67, v181, v12
	v_fmac_f32_e32 v66, v182, v13
	v_fmac_f32_e32 v67, v183, v14
	ds_read_b128 v[180:183], v105 offset:42864
	s_waitcnt lgkmcnt(11)
	v_fmac_f32_e32 v66, v136, v15
	v_fmac_f32_e32 v67, v137, v16
	v_fmac_f32_e32 v66, v138, v17
	v_fmac_f32_e32 v67, v139, v18
	ds_read_b128 v[136:139], v105 offset:43008
	s_waitcnt lgkmcnt(11)
	v_fmac_f32_e32 v66, v140, v20
	v_fmac_f32_e32 v67, v141, v21
	v_fmac_f32_e32 v66, v142, v22
	v_fmac_f32_e32 v67, v143, v23
	ds_read_b128 v[140:143], v105 offset:43024
	s_waitcnt lgkmcnt(11)
	v_fmac_f32_e32 v66, v144, v24
	v_fmac_f32_e32 v67, v145, v25
	v_fmac_f32_e32 v66, v146, v26
	v_fmac_f32_e32 v67, v147, v27
	ds_read_b128 v[144:147], v105 offset:43040
	s_waitcnt lgkmcnt(11)
	v_fmac_f32_e32 v66, v148, v28
	v_fmac_f32_e32 v67, v149, v29
	v_fmac_f32_e32 v66, v150, v30
	v_fmac_f32_e32 v67, v151, v31
	v_sub_f32_e32 v32, v32, v66
	v_sub_f32_e32 v32, v32, v67
	ds_read_b128 v[148:151], v105 offset:43056
	s_waitcnt lgkmcnt(11)
	v_mul_f32_e32 v66, v152, v0
	v_mul_f32_e32 v67, v153, v4
	v_fmac_f32_e32 v66, v154, v5
	v_fmac_f32_e32 v67, v155, v6
	ds_read_b128 v[152:155], v105 offset:43072
	s_waitcnt lgkmcnt(11)
	v_fmac_f32_e32 v66, v156, v7
	v_fmac_f32_e32 v67, v157, v8
	v_fmac_f32_e32 v66, v158, v9
	v_fmac_f32_e32 v67, v159, v10
	ds_read_b128 v[156:159], v105 offset:43088
	s_waitcnt lgkmcnt(11)
	v_fmac_f32_e32 v66, v160, v11
	v_fmac_f32_e32 v67, v161, v12
	v_fmac_f32_e32 v66, v162, v13
	v_fmac_f32_e32 v67, v163, v14
	ds_read_b128 v[160:163], v105 offset:43104
	s_waitcnt lgkmcnt(11)
	v_fmac_f32_e32 v66, v164, v15
	v_fmac_f32_e32 v67, v165, v16
	v_fmac_f32_e32 v66, v166, v17
	v_fmac_f32_e32 v67, v167, v18
	ds_read_b128 v[164:167], v105 offset:43120
	s_waitcnt lgkmcnt(11)
	v_fmac_f32_e32 v66, v168, v20
	v_fmac_f32_e32 v67, v169, v21
	v_fmac_f32_e32 v66, v170, v22
	v_fmac_f32_e32 v67, v171, v23
	ds_read_b128 v[168:171], v105 offset:43264
	s_waitcnt lgkmcnt(11)
	v_fmac_f32_e32 v66, v172, v24
	v_fmac_f32_e32 v67, v173, v25
	v_fmac_f32_e32 v66, v174, v26
	v_fmac_f32_e32 v67, v175, v27
	ds_read_b128 v[172:175], v105 offset:43280
	s_waitcnt lgkmcnt(11)
	v_fmac_f32_e32 v66, v176, v28
	v_fmac_f32_e32 v67, v177, v29
	v_fmac_f32_e32 v66, v178, v30
	v_fmac_f32_e32 v67, v179, v31
	ds_read_b128 v[176:179], v105 offset:43296
	s_waitcnt lgkmcnt(11)
	v_fmac_f32_e32 v66, v180, v32
	v_sub_f32_e32 v33, v33, v66
	v_sub_f32_e32 v33, v33, v67
	ds_read_b128 v[180:183], v105 offset:43312
	s_waitcnt lgkmcnt(11)
	v_mul_f32_e32 v66, v136, v0
	v_mul_f32_e32 v67, v137, v4
	v_fmac_f32_e32 v66, v138, v5
	v_fmac_f32_e32 v67, v139, v6
	ds_read_b128 v[136:139], v105 offset:43328
	s_waitcnt lgkmcnt(11)
	v_fmac_f32_e32 v66, v140, v7
	v_fmac_f32_e32 v67, v141, v8
	v_fmac_f32_e32 v66, v142, v9
	v_fmac_f32_e32 v67, v143, v10
	ds_read_b128 v[140:143], v105 offset:43344
	s_waitcnt lgkmcnt(11)
	v_fmac_f32_e32 v66, v144, v11
	v_fmac_f32_e32 v67, v145, v12
	v_fmac_f32_e32 v66, v146, v13
	v_fmac_f32_e32 v67, v147, v14
	ds_read_b128 v[144:147], v105 offset:43360
	s_waitcnt lgkmcnt(11)
	v_fmac_f32_e32 v66, v148, v15
	v_fmac_f32_e32 v67, v149, v16
	v_fmac_f32_e32 v66, v150, v17
	v_fmac_f32_e32 v67, v151, v18
	ds_read_b128 v[148:151], v105 offset:43376
	s_waitcnt lgkmcnt(11)
	v_fmac_f32_e32 v66, v152, v20
	v_fmac_f32_e32 v67, v153, v21
	v_fmac_f32_e32 v66, v154, v22
	v_fmac_f32_e32 v67, v155, v23
	ds_read_b128 v[152:155], v105 offset:43520
	s_waitcnt lgkmcnt(11)
	v_fmac_f32_e32 v66, v156, v24
	v_fmac_f32_e32 v67, v157, v25
	v_fmac_f32_e32 v66, v158, v26
	v_fmac_f32_e32 v67, v159, v27
	ds_read_b128 v[156:159], v105 offset:43536
	s_waitcnt lgkmcnt(11)
	v_fmac_f32_e32 v66, v160, v28
	v_fmac_f32_e32 v67, v161, v29
	v_fmac_f32_e32 v66, v162, v30
	v_fmac_f32_e32 v67, v163, v31
	ds_read_b128 v[160:163], v105 offset:43552
	s_waitcnt lgkmcnt(11)
	v_fmac_f32_e32 v66, v164, v32
	v_fmac_f32_e32 v67, v165, v33
	v_sub_f32_e32 v34, v34, v66
	v_sub_f32_e32 v34, v34, v67
	ds_read_b128 v[164:167], v105 offset:43568
	s_waitcnt lgkmcnt(11)
	v_mul_f32_e32 v66, v168, v0
	v_mul_f32_e32 v67, v169, v4
	v_fmac_f32_e32 v66, v170, v5
	v_fmac_f32_e32 v67, v171, v6
	ds_read_b128 v[168:171], v105 offset:43584
	s_waitcnt lgkmcnt(11)
	v_fmac_f32_e32 v66, v172, v7
	v_fmac_f32_e32 v67, v173, v8
	v_fmac_f32_e32 v66, v174, v9
	v_fmac_f32_e32 v67, v175, v10
	ds_read_b128 v[172:175], v105 offset:43600
	s_waitcnt lgkmcnt(11)
	v_fmac_f32_e32 v66, v176, v11
	v_fmac_f32_e32 v67, v177, v12
	v_fmac_f32_e32 v66, v178, v13
	v_fmac_f32_e32 v67, v179, v14
	ds_read_b128 v[176:179], v105 offset:43616
	s_waitcnt lgkmcnt(11)
	v_fmac_f32_e32 v66, v180, v15
	v_fmac_f32_e32 v67, v181, v16
	v_fmac_f32_e32 v66, v182, v17
	v_fmac_f32_e32 v67, v183, v18
	ds_read_b128 v[180:183], v105 offset:43632
	s_waitcnt lgkmcnt(11)
	v_fmac_f32_e32 v66, v136, v20
	v_fmac_f32_e32 v67, v137, v21
	v_fmac_f32_e32 v66, v138, v22
	v_fmac_f32_e32 v67, v139, v23
	ds_read_b128 v[136:139], v105 offset:43776
	s_waitcnt lgkmcnt(11)
	v_fmac_f32_e32 v66, v140, v24
	v_fmac_f32_e32 v67, v141, v25
	v_fmac_f32_e32 v66, v142, v26
	v_fmac_f32_e32 v67, v143, v27
	ds_read_b128 v[140:143], v105 offset:43792
	s_waitcnt lgkmcnt(11)
	v_fmac_f32_e32 v66, v144, v28
	v_fmac_f32_e32 v67, v145, v29
	v_fmac_f32_e32 v66, v146, v30
	v_fmac_f32_e32 v67, v147, v31
	ds_read_b128 v[144:147], v105 offset:43808
	s_waitcnt lgkmcnt(11)
	v_fmac_f32_e32 v66, v148, v32
	v_fmac_f32_e32 v67, v149, v33
	v_fmac_f32_e32 v66, v150, v34
	v_sub_f32_e32 v35, v35, v66
	v_sub_f32_e32 v35, v35, v67
	ds_read_b128 v[148:151], v105 offset:43824
	s_waitcnt lgkmcnt(11)
	v_mul_f32_e32 v66, v152, v0
	v_mul_f32_e32 v67, v153, v4
	v_fmac_f32_e32 v66, v154, v5
	v_fmac_f32_e32 v67, v155, v6
	ds_read_b128 v[152:155], v105 offset:43840
	s_waitcnt lgkmcnt(11)
	v_fmac_f32_e32 v66, v156, v7
	v_fmac_f32_e32 v67, v157, v8
	v_fmac_f32_e32 v66, v158, v9
	v_fmac_f32_e32 v67, v159, v10
	ds_read_b128 v[156:159], v105 offset:43856
	s_waitcnt lgkmcnt(11)
	v_fmac_f32_e32 v66, v160, v11
	v_fmac_f32_e32 v67, v161, v12
	v_fmac_f32_e32 v66, v162, v13
	v_fmac_f32_e32 v67, v163, v14
	ds_read_b128 v[160:163], v105 offset:43872
	s_waitcnt lgkmcnt(11)
	v_fmac_f32_e32 v66, v164, v15
	v_fmac_f32_e32 v67, v165, v16
	v_fmac_f32_e32 v66, v166, v17
	v_fmac_f32_e32 v67, v167, v18
	ds_read_b128 v[164:167], v105 offset:43888
	s_waitcnt lgkmcnt(11)
	v_fmac_f32_e32 v66, v168, v20
	v_fmac_f32_e32 v67, v169, v21
	v_fmac_f32_e32 v66, v170, v22
	v_fmac_f32_e32 v67, v171, v23
	ds_read_b128 v[168:171], v105 offset:43904
	s_waitcnt lgkmcnt(11)
	v_fmac_f32_e32 v66, v172, v24
	v_fmac_f32_e32 v67, v173, v25
	v_fmac_f32_e32 v66, v174, v26
	v_fmac_f32_e32 v67, v175, v27
	ds_read_b128 v[172:175], v105 offset:44032
	s_waitcnt lgkmcnt(11)
	v_fmac_f32_e32 v66, v176, v28
	v_fmac_f32_e32 v67, v177, v29
	v_fmac_f32_e32 v66, v178, v30
	v_fmac_f32_e32 v67, v179, v31
	ds_read_b128 v[176:179], v105 offset:44048
	s_waitcnt lgkmcnt(11)
	v_fmac_f32_e32 v66, v180, v32
	v_fmac_f32_e32 v67, v181, v33
	v_fmac_f32_e32 v66, v182, v34
	v_fmac_f32_e32 v67, v183, v35
	v_sub_f32_e32 v36, v36, v66
	v_sub_f32_e32 v36, v36, v67
	ds_read_b128 v[180:183], v105 offset:44064
	s_waitcnt lgkmcnt(11)
	v_mul_f32_e32 v66, v136, v0
	v_mul_f32_e32 v67, v137, v4
	v_fmac_f32_e32 v66, v138, v5
	v_fmac_f32_e32 v67, v139, v6
	ds_read_b128 v[136:139], v105 offset:44080
	s_waitcnt lgkmcnt(11)
	v_fmac_f32_e32 v66, v140, v7
	v_fmac_f32_e32 v67, v141, v8
	v_fmac_f32_e32 v66, v142, v9
	v_fmac_f32_e32 v67, v143, v10
	ds_read_b128 v[140:143], v105 offset:44096
	s_waitcnt lgkmcnt(11)
	v_fmac_f32_e32 v66, v144, v11
	v_fmac_f32_e32 v67, v145, v12
	v_fmac_f32_e32 v66, v146, v13
	v_fmac_f32_e32 v67, v147, v14
	ds_read_b128 v[144:147], v105 offset:44112
	s_waitcnt lgkmcnt(11)
	v_fmac_f32_e32 v66, v148, v15
	v_fmac_f32_e32 v67, v149, v16
	v_fmac_f32_e32 v66, v150, v17
	v_fmac_f32_e32 v67, v151, v18
	ds_read_b128 v[148:151], v105 offset:44128
	s_waitcnt lgkmcnt(11)
	v_fmac_f32_e32 v66, v152, v20
	v_fmac_f32_e32 v67, v153, v21
	v_fmac_f32_e32 v66, v154, v22
	v_fmac_f32_e32 v67, v155, v23
	ds_read_b128 v[152:155], v105 offset:44144
	s_waitcnt lgkmcnt(11)
	v_fmac_f32_e32 v66, v156, v24
	v_fmac_f32_e32 v67, v157, v25
	v_fmac_f32_e32 v66, v158, v26
	v_fmac_f32_e32 v67, v159, v27
	ds_read_b128 v[156:159], v105 offset:44160
	s_waitcnt lgkmcnt(11)
	v_fmac_f32_e32 v66, v160, v28
	v_fmac_f32_e32 v67, v161, v29
	v_fmac_f32_e32 v66, v162, v30
	v_fmac_f32_e32 v67, v163, v31
	ds_read_b128 v[160:163], v105 offset:44288
	s_waitcnt lgkmcnt(11)
	v_fmac_f32_e32 v66, v164, v32
	v_fmac_f32_e32 v67, v165, v33
	v_fmac_f32_e32 v66, v166, v34
	v_fmac_f32_e32 v67, v167, v35
	ds_read_b128 v[164:167], v105 offset:44304
	s_waitcnt lgkmcnt(11)
	v_fmac_f32_e32 v66, v168, v36
	v_sub_f32_e32 v37, v37, v66
	v_sub_f32_e32 v37, v37, v67
	ds_read_b128 v[168:171], v105 offset:44320
	s_waitcnt lgkmcnt(11)
	v_mul_f32_e32 v66, v172, v0
	v_mul_f32_e32 v67, v173, v4
	v_fmac_f32_e32 v66, v174, v5
	v_fmac_f32_e32 v67, v175, v6
	ds_read_b128 v[172:175], v105 offset:44336
	s_waitcnt lgkmcnt(11)
	v_fmac_f32_e32 v66, v176, v7
	v_fmac_f32_e32 v67, v177, v8
	v_fmac_f32_e32 v66, v178, v9
	v_fmac_f32_e32 v67, v179, v10
	ds_read_b128 v[176:179], v105 offset:44352
	s_waitcnt lgkmcnt(11)
	v_fmac_f32_e32 v66, v180, v11
	v_fmac_f32_e32 v67, v181, v12
	v_fmac_f32_e32 v66, v182, v13
	v_fmac_f32_e32 v67, v183, v14
	ds_read_b128 v[180:183], v105 offset:44368
	s_waitcnt lgkmcnt(11)
	v_fmac_f32_e32 v66, v136, v15
	v_fmac_f32_e32 v67, v137, v16
	v_fmac_f32_e32 v66, v138, v17
	v_fmac_f32_e32 v67, v139, v18
	ds_read_b128 v[136:139], v105 offset:44384
	s_waitcnt lgkmcnt(11)
	v_fmac_f32_e32 v66, v140, v20
	v_fmac_f32_e32 v67, v141, v21
	v_fmac_f32_e32 v66, v142, v22
	v_fmac_f32_e32 v67, v143, v23
	ds_read_b128 v[140:143], v105 offset:44400
	s_waitcnt lgkmcnt(11)
	v_fmac_f32_e32 v66, v144, v24
	v_fmac_f32_e32 v67, v145, v25
	v_fmac_f32_e32 v66, v146, v26
	v_fmac_f32_e32 v67, v147, v27
	ds_read_b128 v[144:147], v105 offset:44416
	s_waitcnt lgkmcnt(11)
	v_fmac_f32_e32 v66, v148, v28
	v_fmac_f32_e32 v67, v149, v29
	v_fmac_f32_e32 v66, v150, v30
	v_fmac_f32_e32 v67, v151, v31
	ds_read_b128 v[148:151], v105 offset:44544
	s_waitcnt lgkmcnt(11)
	v_fmac_f32_e32 v66, v152, v32
	v_fmac_f32_e32 v67, v153, v33
	v_fmac_f32_e32 v66, v154, v34
	v_fmac_f32_e32 v67, v155, v35
	ds_read_b128 v[152:155], v105 offset:44560
	s_waitcnt lgkmcnt(11)
	v_fmac_f32_e32 v66, v156, v36
	v_fmac_f32_e32 v67, v157, v37
	v_sub_f32_e32 v38, v38, v66
	v_sub_f32_e32 v38, v38, v67
	ds_read_b128 v[156:159], v105 offset:44576
	s_waitcnt lgkmcnt(11)
	v_mul_f32_e32 v66, v160, v0
	v_mul_f32_e32 v67, v161, v4
	v_fmac_f32_e32 v66, v162, v5
	v_fmac_f32_e32 v67, v163, v6
	ds_read_b128 v[160:163], v105 offset:44592
	s_waitcnt lgkmcnt(11)
	v_fmac_f32_e32 v66, v164, v7
	v_fmac_f32_e32 v67, v165, v8
	v_fmac_f32_e32 v66, v166, v9
	v_fmac_f32_e32 v67, v167, v10
	ds_read_b128 v[164:167], v105 offset:44608
	s_waitcnt lgkmcnt(11)
	v_fmac_f32_e32 v66, v168, v11
	v_fmac_f32_e32 v67, v169, v12
	v_fmac_f32_e32 v66, v170, v13
	v_fmac_f32_e32 v67, v171, v14
	ds_read_b128 v[168:171], v105 offset:44624
	s_waitcnt lgkmcnt(11)
	v_fmac_f32_e32 v66, v172, v15
	v_fmac_f32_e32 v67, v173, v16
	v_fmac_f32_e32 v66, v174, v17
	v_fmac_f32_e32 v67, v175, v18
	ds_read_b128 v[172:175], v105 offset:44640
	s_waitcnt lgkmcnt(11)
	v_fmac_f32_e32 v66, v176, v20
	v_fmac_f32_e32 v67, v177, v21
	v_fmac_f32_e32 v66, v178, v22
	v_fmac_f32_e32 v67, v179, v23
	ds_read_b128 v[176:179], v105 offset:44656
	s_waitcnt lgkmcnt(11)
	v_fmac_f32_e32 v66, v180, v24
	v_fmac_f32_e32 v67, v181, v25
	v_fmac_f32_e32 v66, v182, v26
	v_fmac_f32_e32 v67, v183, v27
	ds_read_b128 v[180:183], v105 offset:44672
	s_waitcnt lgkmcnt(11)
	v_fmac_f32_e32 v66, v136, v28
	v_fmac_f32_e32 v67, v137, v29
	v_fmac_f32_e32 v66, v138, v30
	v_fmac_f32_e32 v67, v139, v31
	ds_read_b128 v[136:139], v105 offset:44800
	s_waitcnt lgkmcnt(11)
	v_fmac_f32_e32 v66, v140, v32
	v_fmac_f32_e32 v67, v141, v33
	v_fmac_f32_e32 v66, v142, v34
	v_fmac_f32_e32 v67, v143, v35
	ds_read_b128 v[140:143], v105 offset:44816
	s_waitcnt lgkmcnt(11)
	v_fmac_f32_e32 v66, v144, v36
	v_fmac_f32_e32 v67, v145, v37
	v_fmac_f32_e32 v66, v146, v38
	v_sub_f32_e32 v39, v39, v66
	v_sub_f32_e32 v39, v39, v67
	ds_read_b128 v[144:147], v105 offset:44832
	s_waitcnt lgkmcnt(11)
	v_mul_f32_e32 v66, v148, v0
	v_mul_f32_e32 v67, v149, v4
	v_fmac_f32_e32 v66, v150, v5
	v_fmac_f32_e32 v67, v151, v6
	ds_read_b128 v[148:151], v105 offset:44848
	s_waitcnt lgkmcnt(11)
	v_fmac_f32_e32 v66, v152, v7
	v_fmac_f32_e32 v67, v153, v8
	v_fmac_f32_e32 v66, v154, v9
	v_fmac_f32_e32 v67, v155, v10
	ds_read_b128 v[152:155], v105 offset:44864
	s_waitcnt lgkmcnt(11)
	v_fmac_f32_e32 v66, v156, v11
	v_fmac_f32_e32 v67, v157, v12
	v_fmac_f32_e32 v66, v158, v13
	v_fmac_f32_e32 v67, v159, v14
	ds_read_b128 v[156:159], v105 offset:44880
	s_waitcnt lgkmcnt(11)
	v_fmac_f32_e32 v66, v160, v15
	v_fmac_f32_e32 v67, v161, v16
	v_fmac_f32_e32 v66, v162, v17
	v_fmac_f32_e32 v67, v163, v18
	ds_read_b128 v[160:163], v105 offset:44896
	s_waitcnt lgkmcnt(11)
	v_fmac_f32_e32 v66, v164, v20
	v_fmac_f32_e32 v67, v165, v21
	v_fmac_f32_e32 v66, v166, v22
	v_fmac_f32_e32 v67, v167, v23
	ds_read_b128 v[164:167], v105 offset:44912
	s_waitcnt lgkmcnt(11)
	v_fmac_f32_e32 v66, v168, v24
	v_fmac_f32_e32 v67, v169, v25
	v_fmac_f32_e32 v66, v170, v26
	v_fmac_f32_e32 v67, v171, v27
	ds_read_b128 v[168:171], v105 offset:44928
	s_waitcnt lgkmcnt(11)
	v_fmac_f32_e32 v66, v172, v28
	v_fmac_f32_e32 v67, v173, v29
	v_fmac_f32_e32 v66, v174, v30
	v_fmac_f32_e32 v67, v175, v31
	ds_read_b128 v[172:175], v105 offset:44944
	s_waitcnt lgkmcnt(11)
	v_fmac_f32_e32 v66, v176, v32
	v_fmac_f32_e32 v67, v177, v33
	v_fmac_f32_e32 v66, v178, v34
	v_fmac_f32_e32 v67, v179, v35
	ds_read_b128 v[176:179], v105 offset:45056
	s_waitcnt lgkmcnt(11)
	v_fmac_f32_e32 v66, v180, v36
	v_fmac_f32_e32 v67, v181, v37
	v_fmac_f32_e32 v66, v182, v38
	v_fmac_f32_e32 v67, v183, v39
	v_sub_f32_e32 v40, v40, v66
	v_sub_f32_e32 v40, v40, v67
	ds_read_b128 v[180:183], v105 offset:45072
	s_waitcnt lgkmcnt(11)
	v_mul_f32_e32 v66, v136, v0
	v_mul_f32_e32 v67, v137, v4
	v_fmac_f32_e32 v66, v138, v5
	v_fmac_f32_e32 v67, v139, v6
	ds_read_b128 v[136:139], v105 offset:45088
	s_waitcnt lgkmcnt(11)
	v_fmac_f32_e32 v66, v140, v7
	v_fmac_f32_e32 v67, v141, v8
	v_fmac_f32_e32 v66, v142, v9
	v_fmac_f32_e32 v67, v143, v10
	ds_read_b128 v[140:143], v105 offset:45104
	s_waitcnt lgkmcnt(11)
	v_fmac_f32_e32 v66, v144, v11
	v_fmac_f32_e32 v67, v145, v12
	v_fmac_f32_e32 v66, v146, v13
	v_fmac_f32_e32 v67, v147, v14
	ds_read_b128 v[144:147], v105 offset:45120
	s_waitcnt lgkmcnt(11)
	v_fmac_f32_e32 v66, v148, v15
	v_fmac_f32_e32 v67, v149, v16
	v_fmac_f32_e32 v66, v150, v17
	v_fmac_f32_e32 v67, v151, v18
	ds_read_b128 v[148:151], v105 offset:45136
	s_waitcnt lgkmcnt(11)
	v_fmac_f32_e32 v66, v152, v20
	v_fmac_f32_e32 v67, v153, v21
	v_fmac_f32_e32 v66, v154, v22
	v_fmac_f32_e32 v67, v155, v23
	ds_read_b128 v[152:155], v105 offset:45152
	s_waitcnt lgkmcnt(11)
	v_fmac_f32_e32 v66, v156, v24
	v_fmac_f32_e32 v67, v157, v25
	v_fmac_f32_e32 v66, v158, v26
	v_fmac_f32_e32 v67, v159, v27
	ds_read_b128 v[156:159], v105 offset:45168
	s_waitcnt lgkmcnt(11)
	v_fmac_f32_e32 v66, v160, v28
	v_fmac_f32_e32 v67, v161, v29
	v_fmac_f32_e32 v66, v162, v30
	v_fmac_f32_e32 v67, v163, v31
	ds_read_b128 v[160:163], v105 offset:45184
	s_waitcnt lgkmcnt(11)
	v_fmac_f32_e32 v66, v164, v32
	v_fmac_f32_e32 v67, v165, v33
	v_fmac_f32_e32 v66, v166, v34
	v_fmac_f32_e32 v67, v167, v35
	ds_read_b128 v[164:167], v105 offset:45200
	s_waitcnt lgkmcnt(11)
	v_fmac_f32_e32 v66, v168, v36
	v_fmac_f32_e32 v67, v169, v37
	v_fmac_f32_e32 v66, v170, v38
	v_fmac_f32_e32 v67, v171, v39
	ds_read_b128 v[168:171], v105 offset:45312
	s_waitcnt lgkmcnt(11)
	v_fmac_f32_e32 v66, v172, v40
	v_sub_f32_e32 v41, v41, v66
	v_sub_f32_e32 v41, v41, v67
	ds_read_b128 v[172:175], v105 offset:45328
	s_waitcnt lgkmcnt(11)
	v_mul_f32_e32 v66, v176, v0
	v_mul_f32_e32 v67, v177, v4
	v_fmac_f32_e32 v66, v178, v5
	v_fmac_f32_e32 v67, v179, v6
	ds_read_b128 v[176:179], v105 offset:45344
	s_waitcnt lgkmcnt(11)
	v_fmac_f32_e32 v66, v180, v7
	v_fmac_f32_e32 v67, v181, v8
	v_fmac_f32_e32 v66, v182, v9
	v_fmac_f32_e32 v67, v183, v10
	ds_read_b128 v[180:183], v105 offset:45360
	s_waitcnt lgkmcnt(11)
	v_fmac_f32_e32 v66, v136, v11
	v_fmac_f32_e32 v67, v137, v12
	v_fmac_f32_e32 v66, v138, v13
	v_fmac_f32_e32 v67, v139, v14
	ds_read_b128 v[136:139], v105 offset:45376
	s_waitcnt lgkmcnt(11)
	v_fmac_f32_e32 v66, v140, v15
	v_fmac_f32_e32 v67, v141, v16
	v_fmac_f32_e32 v66, v142, v17
	v_fmac_f32_e32 v67, v143, v18
	ds_read_b128 v[140:143], v105 offset:45392
	s_waitcnt lgkmcnt(11)
	v_fmac_f32_e32 v66, v144, v20
	v_fmac_f32_e32 v67, v145, v21
	v_fmac_f32_e32 v66, v146, v22
	v_fmac_f32_e32 v67, v147, v23
	ds_read_b128 v[144:147], v105 offset:45408
	s_waitcnt lgkmcnt(11)
	v_fmac_f32_e32 v66, v148, v24
	v_fmac_f32_e32 v67, v149, v25
	v_fmac_f32_e32 v66, v150, v26
	v_fmac_f32_e32 v67, v151, v27
	ds_read_b128 v[148:151], v105 offset:45424
	s_waitcnt lgkmcnt(11)
	v_fmac_f32_e32 v66, v152, v28
	v_fmac_f32_e32 v67, v153, v29
	v_fmac_f32_e32 v66, v154, v30
	v_fmac_f32_e32 v67, v155, v31
	ds_read_b128 v[152:155], v105 offset:45440
	s_waitcnt lgkmcnt(11)
	v_fmac_f32_e32 v66, v156, v32
	v_fmac_f32_e32 v67, v157, v33
	v_fmac_f32_e32 v66, v158, v34
	v_fmac_f32_e32 v67, v159, v35
	ds_read_b128 v[156:159], v105 offset:45456
	s_waitcnt lgkmcnt(11)
	v_fmac_f32_e32 v66, v160, v36
	v_fmac_f32_e32 v67, v161, v37
	v_fmac_f32_e32 v66, v162, v38
	v_fmac_f32_e32 v67, v163, v39
	ds_read_b128 v[160:163], v105 offset:45568
	s_waitcnt lgkmcnt(11)
	v_fmac_f32_e32 v66, v164, v40
	v_fmac_f32_e32 v67, v165, v41
	v_sub_f32_e32 v42, v42, v66
	v_sub_f32_e32 v42, v42, v67
	ds_read_b128 v[164:167], v105 offset:45584
	s_waitcnt lgkmcnt(11)
	v_mul_f32_e32 v66, v168, v0
	v_mul_f32_e32 v67, v169, v4
	v_fmac_f32_e32 v66, v170, v5
	v_fmac_f32_e32 v67, v171, v6
	ds_read_b128 v[168:171], v105 offset:45600
	s_waitcnt lgkmcnt(11)
	v_fmac_f32_e32 v66, v172, v7
	v_fmac_f32_e32 v67, v173, v8
	v_fmac_f32_e32 v66, v174, v9
	v_fmac_f32_e32 v67, v175, v10
	ds_read_b128 v[172:175], v105 offset:45616
	s_waitcnt lgkmcnt(11)
	v_fmac_f32_e32 v66, v176, v11
	v_fmac_f32_e32 v67, v177, v12
	v_fmac_f32_e32 v66, v178, v13
	v_fmac_f32_e32 v67, v179, v14
	ds_read_b128 v[176:179], v105 offset:45632
	s_waitcnt lgkmcnt(11)
	v_fmac_f32_e32 v66, v180, v15
	v_fmac_f32_e32 v67, v181, v16
	v_fmac_f32_e32 v66, v182, v17
	v_fmac_f32_e32 v67, v183, v18
	ds_read_b128 v[180:183], v105 offset:45648
	s_waitcnt lgkmcnt(11)
	v_fmac_f32_e32 v66, v136, v20
	v_fmac_f32_e32 v67, v137, v21
	v_fmac_f32_e32 v66, v138, v22
	v_fmac_f32_e32 v67, v139, v23
	ds_read_b128 v[136:139], v105 offset:45664
	s_waitcnt lgkmcnt(11)
	v_fmac_f32_e32 v66, v140, v24
	v_fmac_f32_e32 v67, v141, v25
	v_fmac_f32_e32 v66, v142, v26
	v_fmac_f32_e32 v67, v143, v27
	ds_read_b128 v[140:143], v105 offset:45680
	s_waitcnt lgkmcnt(11)
	v_fmac_f32_e32 v66, v144, v28
	v_fmac_f32_e32 v67, v145, v29
	v_fmac_f32_e32 v66, v146, v30
	v_fmac_f32_e32 v67, v147, v31
	ds_read_b128 v[144:147], v105 offset:45696
	s_waitcnt lgkmcnt(11)
	v_fmac_f32_e32 v66, v148, v32
	v_fmac_f32_e32 v67, v149, v33
	v_fmac_f32_e32 v66, v150, v34
	v_fmac_f32_e32 v67, v151, v35
	ds_read_b128 v[148:151], v105 offset:45712
	s_waitcnt lgkmcnt(11)
	v_fmac_f32_e32 v66, v152, v36
	v_fmac_f32_e32 v67, v153, v37
	v_fmac_f32_e32 v66, v154, v38
	v_fmac_f32_e32 v67, v155, v39
	ds_read_b128 v[152:155], v105 offset:45824
	s_waitcnt lgkmcnt(11)
	v_fmac_f32_e32 v66, v156, v40
	v_fmac_f32_e32 v67, v157, v41
	v_fmac_f32_e32 v66, v158, v42
	v_sub_f32_e32 v43, v43, v66
	v_sub_f32_e32 v43, v43, v67
	ds_read_b128 v[156:159], v105 offset:45840
	s_waitcnt lgkmcnt(11)
	v_mul_f32_e32 v66, v160, v0
	v_mul_f32_e32 v67, v161, v4
	v_fmac_f32_e32 v66, v162, v5
	v_fmac_f32_e32 v67, v163, v6
	ds_read_b128 v[160:163], v105 offset:45856
	s_waitcnt lgkmcnt(11)
	v_fmac_f32_e32 v66, v164, v7
	v_fmac_f32_e32 v67, v165, v8
	v_fmac_f32_e32 v66, v166, v9
	v_fmac_f32_e32 v67, v167, v10
	ds_read_b128 v[164:167], v105 offset:45872
	s_waitcnt lgkmcnt(11)
	v_fmac_f32_e32 v66, v168, v11
	v_fmac_f32_e32 v67, v169, v12
	v_fmac_f32_e32 v66, v170, v13
	v_fmac_f32_e32 v67, v171, v14
	ds_read_b128 v[168:171], v105 offset:45888
	s_waitcnt lgkmcnt(11)
	v_fmac_f32_e32 v66, v172, v15
	v_fmac_f32_e32 v67, v173, v16
	v_fmac_f32_e32 v66, v174, v17
	v_fmac_f32_e32 v67, v175, v18
	ds_read_b128 v[172:175], v105 offset:45904
	s_waitcnt lgkmcnt(11)
	v_fmac_f32_e32 v66, v176, v20
	v_fmac_f32_e32 v67, v177, v21
	v_fmac_f32_e32 v66, v178, v22
	v_fmac_f32_e32 v67, v179, v23
	ds_read_b128 v[176:179], v105 offset:45920
	s_waitcnt lgkmcnt(11)
	v_fmac_f32_e32 v66, v180, v24
	v_fmac_f32_e32 v67, v181, v25
	v_fmac_f32_e32 v66, v182, v26
	v_fmac_f32_e32 v67, v183, v27
	ds_read_b128 v[180:183], v105 offset:45936
	s_waitcnt lgkmcnt(11)
	v_fmac_f32_e32 v66, v136, v28
	v_fmac_f32_e32 v67, v137, v29
	v_fmac_f32_e32 v66, v138, v30
	v_fmac_f32_e32 v67, v139, v31
	ds_read_b128 v[136:139], v105 offset:45952
	s_waitcnt lgkmcnt(11)
	v_fmac_f32_e32 v66, v140, v32
	v_fmac_f32_e32 v67, v141, v33
	v_fmac_f32_e32 v66, v142, v34
	v_fmac_f32_e32 v67, v143, v35
	ds_read_b128 v[140:143], v105 offset:45968
	s_waitcnt lgkmcnt(11)
	v_fmac_f32_e32 v66, v144, v36
	v_fmac_f32_e32 v67, v145, v37
	v_fmac_f32_e32 v66, v146, v38
	v_fmac_f32_e32 v67, v147, v39
	ds_read_b128 v[144:147], v105 offset:45984
	s_waitcnt lgkmcnt(11)
	v_fmac_f32_e32 v66, v148, v40
	v_fmac_f32_e32 v67, v149, v41
	v_fmac_f32_e32 v66, v150, v42
	v_fmac_f32_e32 v67, v151, v43
	v_sub_f32_e32 v44, v44, v66
	v_sub_f32_e32 v44, v44, v67
	ds_read_b128 v[148:151], v105 offset:46080
	s_waitcnt lgkmcnt(11)
	v_mul_f32_e32 v66, v152, v0
	v_mul_f32_e32 v67, v153, v4
	v_fmac_f32_e32 v66, v154, v5
	v_fmac_f32_e32 v67, v155, v6
	ds_read_b128 v[152:155], v105 offset:46096
	s_waitcnt lgkmcnt(11)
	v_fmac_f32_e32 v66, v156, v7
	v_fmac_f32_e32 v67, v157, v8
	v_fmac_f32_e32 v66, v158, v9
	v_fmac_f32_e32 v67, v159, v10
	ds_read_b128 v[156:159], v105 offset:46112
	s_waitcnt lgkmcnt(11)
	v_fmac_f32_e32 v66, v160, v11
	v_fmac_f32_e32 v67, v161, v12
	v_fmac_f32_e32 v66, v162, v13
	v_fmac_f32_e32 v67, v163, v14
	ds_read_b128 v[160:163], v105 offset:46128
	s_waitcnt lgkmcnt(11)
	v_fmac_f32_e32 v66, v164, v15
	v_fmac_f32_e32 v67, v165, v16
	v_fmac_f32_e32 v66, v166, v17
	v_fmac_f32_e32 v67, v167, v18
	ds_read_b128 v[164:167], v105 offset:46144
	s_waitcnt lgkmcnt(11)
	v_fmac_f32_e32 v66, v168, v20
	v_fmac_f32_e32 v67, v169, v21
	v_fmac_f32_e32 v66, v170, v22
	v_fmac_f32_e32 v67, v171, v23
	ds_read_b128 v[168:171], v105 offset:46160
	s_waitcnt lgkmcnt(11)
	v_fmac_f32_e32 v66, v172, v24
	v_fmac_f32_e32 v67, v173, v25
	v_fmac_f32_e32 v66, v174, v26
	v_fmac_f32_e32 v67, v175, v27
	ds_read_b128 v[172:175], v105 offset:46176
	s_waitcnt lgkmcnt(11)
	v_fmac_f32_e32 v66, v176, v28
	v_fmac_f32_e32 v67, v177, v29
	v_fmac_f32_e32 v66, v178, v30
	v_fmac_f32_e32 v67, v179, v31
	ds_read_b128 v[176:179], v105 offset:46192
	s_waitcnt lgkmcnt(11)
	v_fmac_f32_e32 v66, v180, v32
	v_fmac_f32_e32 v67, v181, v33
	v_fmac_f32_e32 v66, v182, v34
	v_fmac_f32_e32 v67, v183, v35
	ds_read_b128 v[180:183], v105 offset:46208
	s_waitcnt lgkmcnt(11)
	v_fmac_f32_e32 v66, v136, v36
	v_fmac_f32_e32 v67, v137, v37
	v_fmac_f32_e32 v66, v138, v38
	v_fmac_f32_e32 v67, v139, v39
	ds_read_b128 v[136:139], v105 offset:46224
	s_waitcnt lgkmcnt(11)
	v_fmac_f32_e32 v66, v140, v40
	v_fmac_f32_e32 v67, v141, v41
	v_fmac_f32_e32 v66, v142, v42
	v_fmac_f32_e32 v67, v143, v43
	ds_read_b128 v[140:143], v105 offset:46240
	s_waitcnt lgkmcnt(11)
	v_fmac_f32_e32 v66, v144, v44
	v_sub_f32_e32 v45, v45, v66
	v_sub_f32_e32 v45, v45, v67
	ds_read_b128 v[144:147], v105 offset:46336
	s_waitcnt lgkmcnt(11)
	v_mul_f32_e32 v66, v148, v0
	v_mul_f32_e32 v67, v149, v4
	v_fmac_f32_e32 v66, v150, v5
	v_fmac_f32_e32 v67, v151, v6
	ds_read_b128 v[148:151], v105 offset:46352
	s_waitcnt lgkmcnt(11)
	v_fmac_f32_e32 v66, v152, v7
	v_fmac_f32_e32 v67, v153, v8
	v_fmac_f32_e32 v66, v154, v9
	v_fmac_f32_e32 v67, v155, v10
	ds_read_b128 v[152:155], v105 offset:46368
	s_waitcnt lgkmcnt(11)
	v_fmac_f32_e32 v66, v156, v11
	v_fmac_f32_e32 v67, v157, v12
	v_fmac_f32_e32 v66, v158, v13
	v_fmac_f32_e32 v67, v159, v14
	ds_read_b128 v[156:159], v105 offset:46384
	s_waitcnt lgkmcnt(11)
	v_fmac_f32_e32 v66, v160, v15
	v_fmac_f32_e32 v67, v161, v16
	v_fmac_f32_e32 v66, v162, v17
	v_fmac_f32_e32 v67, v163, v18
	ds_read_b128 v[160:163], v105 offset:46400
	s_waitcnt lgkmcnt(11)
	v_fmac_f32_e32 v66, v164, v20
	v_fmac_f32_e32 v67, v165, v21
	v_fmac_f32_e32 v66, v166, v22
	v_fmac_f32_e32 v67, v167, v23
	ds_read_b128 v[164:167], v105 offset:46416
	s_waitcnt lgkmcnt(11)
	v_fmac_f32_e32 v66, v168, v24
	v_fmac_f32_e32 v67, v169, v25
	v_fmac_f32_e32 v66, v170, v26
	v_fmac_f32_e32 v67, v171, v27
	ds_read_b128 v[168:171], v105 offset:46432
	s_waitcnt lgkmcnt(11)
	v_fmac_f32_e32 v66, v172, v28
	v_fmac_f32_e32 v67, v173, v29
	v_fmac_f32_e32 v66, v174, v30
	v_fmac_f32_e32 v67, v175, v31
	ds_read_b128 v[172:175], v105 offset:46448
	s_waitcnt lgkmcnt(11)
	v_fmac_f32_e32 v66, v176, v32
	v_fmac_f32_e32 v67, v177, v33
	v_fmac_f32_e32 v66, v178, v34
	v_fmac_f32_e32 v67, v179, v35
	ds_read_b128 v[176:179], v105 offset:46464
	s_waitcnt lgkmcnt(11)
	v_fmac_f32_e32 v66, v180, v36
	v_fmac_f32_e32 v67, v181, v37
	v_fmac_f32_e32 v66, v182, v38
	v_fmac_f32_e32 v67, v183, v39
	ds_read_b128 v[180:183], v105 offset:46480
	s_waitcnt lgkmcnt(11)
	v_fmac_f32_e32 v66, v136, v40
	v_fmac_f32_e32 v67, v137, v41
	v_fmac_f32_e32 v66, v138, v42
	v_fmac_f32_e32 v67, v139, v43
	ds_read_b128 v[136:139], v105 offset:46496
	s_waitcnt lgkmcnt(11)
	v_fmac_f32_e32 v66, v140, v44
	v_fmac_f32_e32 v67, v141, v45
	v_sub_f32_e32 v46, v46, v66
	v_sub_f32_e32 v46, v46, v67
	ds_read_b128 v[140:143], v105 offset:46592
	s_waitcnt lgkmcnt(11)
	v_mul_f32_e32 v66, v144, v0
	v_mul_f32_e32 v67, v145, v4
	v_fmac_f32_e32 v66, v146, v5
	v_fmac_f32_e32 v67, v147, v6
	ds_read_b128 v[144:147], v105 offset:46608
	s_waitcnt lgkmcnt(11)
	v_fmac_f32_e32 v66, v148, v7
	v_fmac_f32_e32 v67, v149, v8
	v_fmac_f32_e32 v66, v150, v9
	v_fmac_f32_e32 v67, v151, v10
	ds_read_b128 v[148:151], v105 offset:46624
	s_waitcnt lgkmcnt(11)
	v_fmac_f32_e32 v66, v152, v11
	v_fmac_f32_e32 v67, v153, v12
	v_fmac_f32_e32 v66, v154, v13
	v_fmac_f32_e32 v67, v155, v14
	ds_read_b128 v[152:155], v105 offset:46640
	s_waitcnt lgkmcnt(11)
	v_fmac_f32_e32 v66, v156, v15
	v_fmac_f32_e32 v67, v157, v16
	v_fmac_f32_e32 v66, v158, v17
	v_fmac_f32_e32 v67, v159, v18
	ds_read_b128 v[156:159], v105 offset:46656
	s_waitcnt lgkmcnt(11)
	v_fmac_f32_e32 v66, v160, v20
	v_fmac_f32_e32 v67, v161, v21
	v_fmac_f32_e32 v66, v162, v22
	v_fmac_f32_e32 v67, v163, v23
	ds_read_b128 v[160:163], v105 offset:46672
	s_waitcnt lgkmcnt(11)
	v_fmac_f32_e32 v66, v164, v24
	v_fmac_f32_e32 v67, v165, v25
	v_fmac_f32_e32 v66, v166, v26
	v_fmac_f32_e32 v67, v167, v27
	ds_read_b128 v[164:167], v105 offset:46688
	s_waitcnt lgkmcnt(11)
	v_fmac_f32_e32 v66, v168, v28
	v_fmac_f32_e32 v67, v169, v29
	v_fmac_f32_e32 v66, v170, v30
	v_fmac_f32_e32 v67, v171, v31
	ds_read_b128 v[168:171], v105 offset:46704
	s_waitcnt lgkmcnt(11)
	v_fmac_f32_e32 v66, v172, v32
	v_fmac_f32_e32 v67, v173, v33
	v_fmac_f32_e32 v66, v174, v34
	v_fmac_f32_e32 v67, v175, v35
	ds_read_b128 v[172:175], v105 offset:46720
	s_waitcnt lgkmcnt(11)
	v_fmac_f32_e32 v66, v176, v36
	v_fmac_f32_e32 v67, v177, v37
	v_fmac_f32_e32 v66, v178, v38
	v_fmac_f32_e32 v67, v179, v39
	ds_read_b128 v[176:179], v105 offset:46736
	s_waitcnt lgkmcnt(11)
	v_fmac_f32_e32 v66, v180, v40
	v_fmac_f32_e32 v67, v181, v41
	v_fmac_f32_e32 v66, v182, v42
	v_fmac_f32_e32 v67, v183, v43
	ds_read_b128 v[180:183], v105 offset:46752
	s_waitcnt lgkmcnt(11)
	v_fmac_f32_e32 v66, v136, v44
	v_fmac_f32_e32 v67, v137, v45
	v_fmac_f32_e32 v66, v138, v46
	v_sub_f32_e32 v47, v47, v66
	v_sub_f32_e32 v47, v47, v67
	ds_read_b128 v[136:139], v105 offset:46848
	s_waitcnt lgkmcnt(11)
	v_mul_f32_e32 v66, v140, v0
	v_mul_f32_e32 v67, v141, v4
	v_fmac_f32_e32 v66, v142, v5
	v_fmac_f32_e32 v67, v143, v6
	ds_read_b128 v[140:143], v105 offset:46864
	s_waitcnt lgkmcnt(11)
	v_fmac_f32_e32 v66, v144, v7
	v_fmac_f32_e32 v67, v145, v8
	v_fmac_f32_e32 v66, v146, v9
	v_fmac_f32_e32 v67, v147, v10
	ds_read_b128 v[144:147], v105 offset:46880
	s_waitcnt lgkmcnt(11)
	v_fmac_f32_e32 v66, v148, v11
	v_fmac_f32_e32 v67, v149, v12
	v_fmac_f32_e32 v66, v150, v13
	v_fmac_f32_e32 v67, v151, v14
	ds_read_b128 v[148:151], v105 offset:46896
	s_waitcnt lgkmcnt(11)
	v_fmac_f32_e32 v66, v152, v15
	v_fmac_f32_e32 v67, v153, v16
	v_fmac_f32_e32 v66, v154, v17
	v_fmac_f32_e32 v67, v155, v18
	ds_read_b128 v[152:155], v105 offset:46912
	s_waitcnt lgkmcnt(11)
	v_fmac_f32_e32 v66, v156, v20
	v_fmac_f32_e32 v67, v157, v21
	v_fmac_f32_e32 v66, v158, v22
	v_fmac_f32_e32 v67, v159, v23
	ds_read_b128 v[156:159], v105 offset:46928
	s_waitcnt lgkmcnt(11)
	v_fmac_f32_e32 v66, v160, v24
	v_fmac_f32_e32 v67, v161, v25
	v_fmac_f32_e32 v66, v162, v26
	v_fmac_f32_e32 v67, v163, v27
	ds_read_b128 v[160:163], v105 offset:46944
	s_waitcnt lgkmcnt(11)
	v_fmac_f32_e32 v66, v164, v28
	v_fmac_f32_e32 v67, v165, v29
	v_fmac_f32_e32 v66, v166, v30
	v_fmac_f32_e32 v67, v167, v31
	ds_read_b128 v[164:167], v105 offset:46960
	s_waitcnt lgkmcnt(11)
	v_fmac_f32_e32 v66, v168, v32
	v_fmac_f32_e32 v67, v169, v33
	v_fmac_f32_e32 v66, v170, v34
	v_fmac_f32_e32 v67, v171, v35
	ds_read_b128 v[168:171], v105 offset:46976
	s_waitcnt lgkmcnt(11)
	v_fmac_f32_e32 v66, v172, v36
	v_fmac_f32_e32 v67, v173, v37
	v_fmac_f32_e32 v66, v174, v38
	v_fmac_f32_e32 v67, v175, v39
	ds_read_b128 v[172:175], v105 offset:46992
	s_waitcnt lgkmcnt(11)
	v_fmac_f32_e32 v66, v176, v40
	v_fmac_f32_e32 v67, v177, v41
	v_fmac_f32_e32 v66, v178, v42
	v_fmac_f32_e32 v67, v179, v43
	ds_read_b128 v[176:179], v105 offset:47008
	s_waitcnt lgkmcnt(11)
	v_fmac_f32_e32 v66, v180, v44
	v_fmac_f32_e32 v67, v181, v45
	v_fmac_f32_e32 v66, v182, v46
	v_fmac_f32_e32 v67, v183, v47
	v_sub_f32_e32 v48, v48, v66
	v_sub_f32_e32 v48, v48, v67
	ds_read_b128 v[180:183], v105 offset:47024
	s_waitcnt lgkmcnt(11)
	v_mul_f32_e32 v66, v136, v0
	v_mul_f32_e32 v67, v137, v4
	v_fmac_f32_e32 v66, v138, v5
	v_fmac_f32_e32 v67, v139, v6
	ds_read_b128 v[136:139], v105 offset:47104
	s_waitcnt lgkmcnt(11)
	v_fmac_f32_e32 v66, v140, v7
	v_fmac_f32_e32 v67, v141, v8
	v_fmac_f32_e32 v66, v142, v9
	v_fmac_f32_e32 v67, v143, v10
	ds_read_b128 v[140:143], v105 offset:47120
	s_waitcnt lgkmcnt(11)
	v_fmac_f32_e32 v66, v144, v11
	v_fmac_f32_e32 v67, v145, v12
	v_fmac_f32_e32 v66, v146, v13
	v_fmac_f32_e32 v67, v147, v14
	ds_read_b128 v[144:147], v105 offset:47136
	s_waitcnt lgkmcnt(11)
	v_fmac_f32_e32 v66, v148, v15
	v_fmac_f32_e32 v67, v149, v16
	v_fmac_f32_e32 v66, v150, v17
	v_fmac_f32_e32 v67, v151, v18
	ds_read_b128 v[148:151], v105 offset:47152
	s_waitcnt lgkmcnt(11)
	v_fmac_f32_e32 v66, v152, v20
	v_fmac_f32_e32 v67, v153, v21
	v_fmac_f32_e32 v66, v154, v22
	v_fmac_f32_e32 v67, v155, v23
	ds_read_b128 v[152:155], v105 offset:47168
	s_waitcnt lgkmcnt(11)
	v_fmac_f32_e32 v66, v156, v24
	v_fmac_f32_e32 v67, v157, v25
	v_fmac_f32_e32 v66, v158, v26
	v_fmac_f32_e32 v67, v159, v27
	ds_read_b128 v[156:159], v105 offset:47184
	s_waitcnt lgkmcnt(11)
	v_fmac_f32_e32 v66, v160, v28
	v_fmac_f32_e32 v67, v161, v29
	v_fmac_f32_e32 v66, v162, v30
	v_fmac_f32_e32 v67, v163, v31
	ds_read_b128 v[160:163], v105 offset:47200
	s_waitcnt lgkmcnt(11)
	v_fmac_f32_e32 v66, v164, v32
	v_fmac_f32_e32 v67, v165, v33
	v_fmac_f32_e32 v66, v166, v34
	v_fmac_f32_e32 v67, v167, v35
	ds_read_b128 v[164:167], v105 offset:47216
	s_waitcnt lgkmcnt(11)
	v_fmac_f32_e32 v66, v168, v36
	v_fmac_f32_e32 v67, v169, v37
	v_fmac_f32_e32 v66, v170, v38
	v_fmac_f32_e32 v67, v171, v39
	ds_read_b128 v[168:171], v105 offset:47232
	s_waitcnt lgkmcnt(11)
	v_fmac_f32_e32 v66, v172, v40
	v_fmac_f32_e32 v67, v173, v41
	v_fmac_f32_e32 v66, v174, v42
	v_fmac_f32_e32 v67, v175, v43
	ds_read_b128 v[172:175], v105 offset:47248
	s_waitcnt lgkmcnt(11)
	v_fmac_f32_e32 v66, v176, v44
	v_fmac_f32_e32 v67, v177, v45
	v_fmac_f32_e32 v66, v178, v46
	v_fmac_f32_e32 v67, v179, v47
	ds_read_b128 v[176:179], v105 offset:47264
	s_waitcnt lgkmcnt(11)
	v_fmac_f32_e32 v66, v180, v48
	v_sub_f32_e32 v49, v49, v66
	v_sub_f32_e32 v49, v49, v67
	ds_read_b128 v[180:183], v105 offset:47280
	s_waitcnt lgkmcnt(11)
	v_mul_f32_e32 v66, v136, v0
	v_mul_f32_e32 v67, v137, v4
	v_fmac_f32_e32 v66, v138, v5
	v_fmac_f32_e32 v67, v139, v6
	ds_read_b128 v[136:139], v105 offset:47360
	s_waitcnt lgkmcnt(11)
	v_fmac_f32_e32 v66, v140, v7
	v_fmac_f32_e32 v67, v141, v8
	v_fmac_f32_e32 v66, v142, v9
	v_fmac_f32_e32 v67, v143, v10
	ds_read_b128 v[140:143], v105 offset:47376
	s_waitcnt lgkmcnt(11)
	v_fmac_f32_e32 v66, v144, v11
	v_fmac_f32_e32 v67, v145, v12
	v_fmac_f32_e32 v66, v146, v13
	v_fmac_f32_e32 v67, v147, v14
	ds_read_b128 v[144:147], v105 offset:47392
	s_waitcnt lgkmcnt(11)
	v_fmac_f32_e32 v66, v148, v15
	v_fmac_f32_e32 v67, v149, v16
	v_fmac_f32_e32 v66, v150, v17
	v_fmac_f32_e32 v67, v151, v18
	ds_read_b128 v[148:151], v105 offset:47408
	s_waitcnt lgkmcnt(11)
	v_fmac_f32_e32 v66, v152, v20
	v_fmac_f32_e32 v67, v153, v21
	v_fmac_f32_e32 v66, v154, v22
	v_fmac_f32_e32 v67, v155, v23
	ds_read_b128 v[152:155], v105 offset:47424
	s_waitcnt lgkmcnt(11)
	v_fmac_f32_e32 v66, v156, v24
	v_fmac_f32_e32 v67, v157, v25
	v_fmac_f32_e32 v66, v158, v26
	v_fmac_f32_e32 v67, v159, v27
	ds_read_b128 v[156:159], v105 offset:47440
	s_waitcnt lgkmcnt(11)
	v_fmac_f32_e32 v66, v160, v28
	v_fmac_f32_e32 v67, v161, v29
	v_fmac_f32_e32 v66, v162, v30
	v_fmac_f32_e32 v67, v163, v31
	ds_read_b128 v[160:163], v105 offset:47456
	s_waitcnt lgkmcnt(11)
	v_fmac_f32_e32 v66, v164, v32
	v_fmac_f32_e32 v67, v165, v33
	v_fmac_f32_e32 v66, v166, v34
	v_fmac_f32_e32 v67, v167, v35
	ds_read_b128 v[164:167], v105 offset:47472
	s_waitcnt lgkmcnt(11)
	v_fmac_f32_e32 v66, v168, v36
	v_fmac_f32_e32 v67, v169, v37
	v_fmac_f32_e32 v66, v170, v38
	v_fmac_f32_e32 v67, v171, v39
	ds_read_b128 v[168:171], v105 offset:47488
	s_waitcnt lgkmcnt(11)
	v_fmac_f32_e32 v66, v172, v40
	v_fmac_f32_e32 v67, v173, v41
	v_fmac_f32_e32 v66, v174, v42
	v_fmac_f32_e32 v67, v175, v43
	ds_read_b128 v[172:175], v105 offset:47504
	s_waitcnt lgkmcnt(11)
	v_fmac_f32_e32 v66, v176, v44
	v_fmac_f32_e32 v67, v177, v45
	v_fmac_f32_e32 v66, v178, v46
	v_fmac_f32_e32 v67, v179, v47
	ds_read_b128 v[176:179], v105 offset:47520
	s_waitcnt lgkmcnt(11)
	v_fmac_f32_e32 v66, v180, v48
	v_fmac_f32_e32 v67, v181, v49
	v_sub_f32_e32 v50, v50, v66
	v_sub_f32_e32 v50, v50, v67
	ds_read_b128 v[180:183], v105 offset:47536
	s_waitcnt lgkmcnt(11)
	v_mul_f32_e32 v66, v136, v0
	v_mul_f32_e32 v67, v137, v4
	v_fmac_f32_e32 v66, v138, v5
	v_fmac_f32_e32 v67, v139, v6
	ds_read_b128 v[136:139], v105 offset:47616
	s_waitcnt lgkmcnt(11)
	v_fmac_f32_e32 v66, v140, v7
	v_fmac_f32_e32 v67, v141, v8
	v_fmac_f32_e32 v66, v142, v9
	v_fmac_f32_e32 v67, v143, v10
	ds_read_b128 v[140:143], v105 offset:47632
	s_waitcnt lgkmcnt(11)
	v_fmac_f32_e32 v66, v144, v11
	v_fmac_f32_e32 v67, v145, v12
	v_fmac_f32_e32 v66, v146, v13
	v_fmac_f32_e32 v67, v147, v14
	ds_read_b128 v[144:147], v105 offset:47648
	s_waitcnt lgkmcnt(11)
	v_fmac_f32_e32 v66, v148, v15
	v_fmac_f32_e32 v67, v149, v16
	v_fmac_f32_e32 v66, v150, v17
	v_fmac_f32_e32 v67, v151, v18
	ds_read_b128 v[148:151], v105 offset:47664
	s_waitcnt lgkmcnt(11)
	v_fmac_f32_e32 v66, v152, v20
	v_fmac_f32_e32 v67, v153, v21
	v_fmac_f32_e32 v66, v154, v22
	v_fmac_f32_e32 v67, v155, v23
	ds_read_b128 v[152:155], v105 offset:47680
	s_waitcnt lgkmcnt(11)
	v_fmac_f32_e32 v66, v156, v24
	v_fmac_f32_e32 v67, v157, v25
	v_fmac_f32_e32 v66, v158, v26
	v_fmac_f32_e32 v67, v159, v27
	ds_read_b128 v[156:159], v105 offset:47696
	s_waitcnt lgkmcnt(11)
	v_fmac_f32_e32 v66, v160, v28
	v_fmac_f32_e32 v67, v161, v29
	v_fmac_f32_e32 v66, v162, v30
	v_fmac_f32_e32 v67, v163, v31
	ds_read_b128 v[160:163], v105 offset:47712
	s_waitcnt lgkmcnt(11)
	v_fmac_f32_e32 v66, v164, v32
	v_fmac_f32_e32 v67, v165, v33
	v_fmac_f32_e32 v66, v166, v34
	v_fmac_f32_e32 v67, v167, v35
	ds_read_b128 v[164:167], v105 offset:47728
	s_waitcnt lgkmcnt(11)
	v_fmac_f32_e32 v66, v168, v36
	v_fmac_f32_e32 v67, v169, v37
	v_fmac_f32_e32 v66, v170, v38
	v_fmac_f32_e32 v67, v171, v39
	ds_read_b128 v[168:171], v105 offset:47744
	s_waitcnt lgkmcnt(11)
	v_fmac_f32_e32 v66, v172, v40
	v_fmac_f32_e32 v67, v173, v41
	v_fmac_f32_e32 v66, v174, v42
	v_fmac_f32_e32 v67, v175, v43
	ds_read_b128 v[172:175], v105 offset:47760
	s_waitcnt lgkmcnt(11)
	v_fmac_f32_e32 v66, v176, v44
	v_fmac_f32_e32 v67, v177, v45
	v_fmac_f32_e32 v66, v178, v46
	v_fmac_f32_e32 v67, v179, v47
	ds_read_b128 v[176:179], v105 offset:47776
	s_waitcnt lgkmcnt(11)
	v_fmac_f32_e32 v66, v180, v48
	v_fmac_f32_e32 v67, v181, v49
	v_fmac_f32_e32 v66, v182, v50
	v_sub_f32_e32 v51, v51, v66
	v_sub_f32_e32 v51, v51, v67
	ds_read_b128 v[180:183], v105 offset:47792
	s_waitcnt lgkmcnt(11)
	v_mul_f32_e32 v66, v136, v0
	v_mul_f32_e32 v67, v137, v4
	v_fmac_f32_e32 v66, v138, v5
	v_fmac_f32_e32 v67, v139, v6
	ds_read_b128 v[136:139], v105 offset:47872
	s_waitcnt lgkmcnt(11)
	v_fmac_f32_e32 v66, v140, v7
	v_fmac_f32_e32 v67, v141, v8
	v_fmac_f32_e32 v66, v142, v9
	v_fmac_f32_e32 v67, v143, v10
	ds_read_b128 v[140:143], v105 offset:47888
	s_waitcnt lgkmcnt(11)
	v_fmac_f32_e32 v66, v144, v11
	v_fmac_f32_e32 v67, v145, v12
	v_fmac_f32_e32 v66, v146, v13
	v_fmac_f32_e32 v67, v147, v14
	ds_read_b128 v[144:147], v105 offset:47904
	s_waitcnt lgkmcnt(11)
	v_fmac_f32_e32 v66, v148, v15
	v_fmac_f32_e32 v67, v149, v16
	v_fmac_f32_e32 v66, v150, v17
	v_fmac_f32_e32 v67, v151, v18
	ds_read_b128 v[148:151], v105 offset:47920
	s_waitcnt lgkmcnt(11)
	v_fmac_f32_e32 v66, v152, v20
	v_fmac_f32_e32 v67, v153, v21
	v_fmac_f32_e32 v66, v154, v22
	v_fmac_f32_e32 v67, v155, v23
	ds_read_b128 v[152:155], v105 offset:47936
	s_waitcnt lgkmcnt(11)
	v_fmac_f32_e32 v66, v156, v24
	v_fmac_f32_e32 v67, v157, v25
	v_fmac_f32_e32 v66, v158, v26
	v_fmac_f32_e32 v67, v159, v27
	ds_read_b128 v[156:159], v105 offset:47952
	s_waitcnt lgkmcnt(11)
	v_fmac_f32_e32 v66, v160, v28
	v_fmac_f32_e32 v67, v161, v29
	v_fmac_f32_e32 v66, v162, v30
	v_fmac_f32_e32 v67, v163, v31
	ds_read_b128 v[160:163], v105 offset:47968
	s_waitcnt lgkmcnt(11)
	v_fmac_f32_e32 v66, v164, v32
	v_fmac_f32_e32 v67, v165, v33
	v_fmac_f32_e32 v66, v166, v34
	v_fmac_f32_e32 v67, v167, v35
	ds_read_b128 v[164:167], v105 offset:47984
	s_waitcnt lgkmcnt(11)
	v_fmac_f32_e32 v66, v168, v36
	v_fmac_f32_e32 v67, v169, v37
	v_fmac_f32_e32 v66, v170, v38
	v_fmac_f32_e32 v67, v171, v39
	ds_read_b128 v[168:171], v105 offset:48000
	s_waitcnt lgkmcnt(11)
	v_fmac_f32_e32 v66, v172, v40
	v_fmac_f32_e32 v67, v173, v41
	v_fmac_f32_e32 v66, v174, v42
	v_fmac_f32_e32 v67, v175, v43
	ds_read_b128 v[172:175], v105 offset:48016
	s_waitcnt lgkmcnt(11)
	v_fmac_f32_e32 v66, v176, v44
	v_fmac_f32_e32 v67, v177, v45
	v_fmac_f32_e32 v66, v178, v46
	v_fmac_f32_e32 v67, v179, v47
	ds_read_b128 v[176:179], v105 offset:48032
	s_waitcnt lgkmcnt(11)
	v_fmac_f32_e32 v66, v180, v48
	v_fmac_f32_e32 v67, v181, v49
	v_fmac_f32_e32 v66, v182, v50
	v_fmac_f32_e32 v67, v183, v51
	v_sub_f32_e32 v52, v52, v66
	v_sub_f32_e32 v52, v52, v67
	ds_read_b128 v[180:183], v105 offset:48048
	s_waitcnt lgkmcnt(11)
	v_mul_f32_e32 v66, v136, v0
	v_mul_f32_e32 v67, v137, v4
	v_fmac_f32_e32 v66, v138, v5
	v_fmac_f32_e32 v67, v139, v6
	ds_read_b128 v[136:139], v105 offset:48064
	s_waitcnt lgkmcnt(11)
	v_fmac_f32_e32 v66, v140, v7
	v_fmac_f32_e32 v67, v141, v8
	v_fmac_f32_e32 v66, v142, v9
	v_fmac_f32_e32 v67, v143, v10
	ds_read_b128 v[140:143], v105 offset:48128
	s_waitcnt lgkmcnt(11)
	v_fmac_f32_e32 v66, v144, v11
	v_fmac_f32_e32 v67, v145, v12
	v_fmac_f32_e32 v66, v146, v13
	v_fmac_f32_e32 v67, v147, v14
	ds_read_b128 v[144:147], v105 offset:48144
	s_waitcnt lgkmcnt(11)
	v_fmac_f32_e32 v66, v148, v15
	v_fmac_f32_e32 v67, v149, v16
	v_fmac_f32_e32 v66, v150, v17
	v_fmac_f32_e32 v67, v151, v18
	ds_read_b128 v[148:151], v105 offset:48160
	s_waitcnt lgkmcnt(11)
	v_fmac_f32_e32 v66, v152, v20
	v_fmac_f32_e32 v67, v153, v21
	v_fmac_f32_e32 v66, v154, v22
	v_fmac_f32_e32 v67, v155, v23
	ds_read_b128 v[152:155], v105 offset:48176
	s_waitcnt lgkmcnt(11)
	v_fmac_f32_e32 v66, v156, v24
	v_fmac_f32_e32 v67, v157, v25
	v_fmac_f32_e32 v66, v158, v26
	v_fmac_f32_e32 v67, v159, v27
	ds_read_b128 v[156:159], v105 offset:48192
	s_waitcnt lgkmcnt(11)
	v_fmac_f32_e32 v66, v160, v28
	v_fmac_f32_e32 v67, v161, v29
	v_fmac_f32_e32 v66, v162, v30
	v_fmac_f32_e32 v67, v163, v31
	ds_read_b128 v[160:163], v105 offset:48208
	s_waitcnt lgkmcnt(11)
	v_fmac_f32_e32 v66, v164, v32
	v_fmac_f32_e32 v67, v165, v33
	v_fmac_f32_e32 v66, v166, v34
	v_fmac_f32_e32 v67, v167, v35
	ds_read_b128 v[164:167], v105 offset:48224
	s_waitcnt lgkmcnt(11)
	v_fmac_f32_e32 v66, v168, v36
	v_fmac_f32_e32 v67, v169, v37
	v_fmac_f32_e32 v66, v170, v38
	v_fmac_f32_e32 v67, v171, v39
	ds_read_b128 v[168:171], v105 offset:48240
	s_waitcnt lgkmcnt(11)
	v_fmac_f32_e32 v66, v172, v40
	v_fmac_f32_e32 v67, v173, v41
	v_fmac_f32_e32 v66, v174, v42
	v_fmac_f32_e32 v67, v175, v43
	ds_read_b128 v[172:175], v105 offset:48256
	s_waitcnt lgkmcnt(11)
	v_fmac_f32_e32 v66, v176, v44
	v_fmac_f32_e32 v67, v177, v45
	v_fmac_f32_e32 v66, v178, v46
	v_fmac_f32_e32 v67, v179, v47
	ds_read_b128 v[176:179], v105 offset:48272
	s_waitcnt lgkmcnt(11)
	v_fmac_f32_e32 v66, v180, v48
	v_fmac_f32_e32 v67, v181, v49
	v_fmac_f32_e32 v66, v182, v50
	v_fmac_f32_e32 v67, v183, v51
	ds_read_b128 v[180:183], v105 offset:48288
	s_waitcnt lgkmcnt(11)
	v_fmac_f32_e32 v66, v136, v52
	v_sub_f32_e32 v53, v53, v66
	v_sub_f32_e32 v53, v53, v67
	ds_read_b128 v[136:139], v105 offset:48304
	s_waitcnt lgkmcnt(11)
	v_mul_f32_e32 v66, v140, v0
	v_mul_f32_e32 v67, v141, v4
	v_fmac_f32_e32 v66, v142, v5
	v_fmac_f32_e32 v67, v143, v6
	ds_read_b128 v[140:143], v105 offset:48320
	s_waitcnt lgkmcnt(11)
	v_fmac_f32_e32 v66, v144, v7
	v_fmac_f32_e32 v67, v145, v8
	v_fmac_f32_e32 v66, v146, v9
	v_fmac_f32_e32 v67, v147, v10
	ds_read_b128 v[144:147], v105 offset:48384
	s_waitcnt lgkmcnt(11)
	v_fmac_f32_e32 v66, v148, v11
	v_fmac_f32_e32 v67, v149, v12
	v_fmac_f32_e32 v66, v150, v13
	v_fmac_f32_e32 v67, v151, v14
	ds_read_b128 v[148:151], v105 offset:48400
	s_waitcnt lgkmcnt(11)
	v_fmac_f32_e32 v66, v152, v15
	v_fmac_f32_e32 v67, v153, v16
	v_fmac_f32_e32 v66, v154, v17
	v_fmac_f32_e32 v67, v155, v18
	ds_read_b128 v[152:155], v105 offset:48416
	s_waitcnt lgkmcnt(11)
	v_fmac_f32_e32 v66, v156, v20
	v_fmac_f32_e32 v67, v157, v21
	v_fmac_f32_e32 v66, v158, v22
	v_fmac_f32_e32 v67, v159, v23
	ds_read_b128 v[156:159], v105 offset:48432
	s_waitcnt lgkmcnt(11)
	v_fmac_f32_e32 v66, v160, v24
	v_fmac_f32_e32 v67, v161, v25
	v_fmac_f32_e32 v66, v162, v26
	v_fmac_f32_e32 v67, v163, v27
	ds_read_b128 v[160:163], v105 offset:48448
	s_waitcnt lgkmcnt(11)
	v_fmac_f32_e32 v66, v164, v28
	v_fmac_f32_e32 v67, v165, v29
	v_fmac_f32_e32 v66, v166, v30
	v_fmac_f32_e32 v67, v167, v31
	ds_read_b128 v[164:167], v105 offset:48464
	s_waitcnt lgkmcnt(11)
	v_fmac_f32_e32 v66, v168, v32
	v_fmac_f32_e32 v67, v169, v33
	v_fmac_f32_e32 v66, v170, v34
	v_fmac_f32_e32 v67, v171, v35
	ds_read_b128 v[168:171], v105 offset:48480
	s_waitcnt lgkmcnt(11)
	v_fmac_f32_e32 v66, v172, v36
	v_fmac_f32_e32 v67, v173, v37
	v_fmac_f32_e32 v66, v174, v38
	v_fmac_f32_e32 v67, v175, v39
	ds_read_b128 v[172:175], v105 offset:48496
	s_waitcnt lgkmcnt(11)
	v_fmac_f32_e32 v66, v176, v40
	v_fmac_f32_e32 v67, v177, v41
	v_fmac_f32_e32 v66, v178, v42
	v_fmac_f32_e32 v67, v179, v43
	ds_read_b128 v[176:179], v105 offset:48512
	s_waitcnt lgkmcnt(11)
	v_fmac_f32_e32 v66, v180, v44
	v_fmac_f32_e32 v67, v181, v45
	v_fmac_f32_e32 v66, v182, v46
	v_fmac_f32_e32 v67, v183, v47
	ds_read_b128 v[180:183], v105 offset:48528
	s_waitcnt lgkmcnt(11)
	v_fmac_f32_e32 v66, v136, v48
	v_fmac_f32_e32 v67, v137, v49
	v_fmac_f32_e32 v66, v138, v50
	v_fmac_f32_e32 v67, v139, v51
	ds_read_b128 v[136:139], v105 offset:48544
	s_waitcnt lgkmcnt(11)
	v_fmac_f32_e32 v66, v140, v52
	v_fmac_f32_e32 v67, v141, v53
	v_sub_f32_e32 v54, v54, v66
	v_sub_f32_e32 v54, v54, v67
	ds_read_b128 v[140:143], v105 offset:48560
	s_waitcnt lgkmcnt(11)
	v_mul_f32_e32 v66, v144, v0
	v_mul_f32_e32 v67, v145, v4
	v_fmac_f32_e32 v66, v146, v5
	v_fmac_f32_e32 v67, v147, v6
	ds_read_b128 v[144:147], v105 offset:48576
	s_waitcnt lgkmcnt(11)
	v_fmac_f32_e32 v66, v148, v7
	v_fmac_f32_e32 v67, v149, v8
	v_fmac_f32_e32 v66, v150, v9
	v_fmac_f32_e32 v67, v151, v10
	ds_read_b128 v[148:151], v105 offset:48640
	s_waitcnt lgkmcnt(11)
	v_fmac_f32_e32 v66, v152, v11
	v_fmac_f32_e32 v67, v153, v12
	v_fmac_f32_e32 v66, v154, v13
	v_fmac_f32_e32 v67, v155, v14
	ds_read_b128 v[152:155], v105 offset:48656
	s_waitcnt lgkmcnt(11)
	v_fmac_f32_e32 v66, v156, v15
	v_fmac_f32_e32 v67, v157, v16
	v_fmac_f32_e32 v66, v158, v17
	v_fmac_f32_e32 v67, v159, v18
	ds_read_b128 v[156:159], v105 offset:48672
	s_waitcnt lgkmcnt(11)
	v_fmac_f32_e32 v66, v160, v20
	v_fmac_f32_e32 v67, v161, v21
	v_fmac_f32_e32 v66, v162, v22
	v_fmac_f32_e32 v67, v163, v23
	ds_read_b128 v[160:163], v105 offset:48688
	s_waitcnt lgkmcnt(11)
	v_fmac_f32_e32 v66, v164, v24
	v_fmac_f32_e32 v67, v165, v25
	v_fmac_f32_e32 v66, v166, v26
	v_fmac_f32_e32 v67, v167, v27
	ds_read_b128 v[164:167], v105 offset:48704
	s_waitcnt lgkmcnt(11)
	v_fmac_f32_e32 v66, v168, v28
	v_fmac_f32_e32 v67, v169, v29
	v_fmac_f32_e32 v66, v170, v30
	v_fmac_f32_e32 v67, v171, v31
	ds_read_b128 v[168:171], v105 offset:48720
	s_waitcnt lgkmcnt(11)
	v_fmac_f32_e32 v66, v172, v32
	v_fmac_f32_e32 v67, v173, v33
	v_fmac_f32_e32 v66, v174, v34
	v_fmac_f32_e32 v67, v175, v35
	ds_read_b128 v[172:175], v105 offset:48736
	s_waitcnt lgkmcnt(11)
	v_fmac_f32_e32 v66, v176, v36
	v_fmac_f32_e32 v67, v177, v37
	v_fmac_f32_e32 v66, v178, v38
	v_fmac_f32_e32 v67, v179, v39
	ds_read_b128 v[176:179], v105 offset:48752
	s_waitcnt lgkmcnt(11)
	v_fmac_f32_e32 v66, v180, v40
	v_fmac_f32_e32 v67, v181, v41
	v_fmac_f32_e32 v66, v182, v42
	v_fmac_f32_e32 v67, v183, v43
	ds_read_b128 v[180:183], v105 offset:48768
	s_waitcnt lgkmcnt(11)
	v_fmac_f32_e32 v66, v136, v44
	v_fmac_f32_e32 v67, v137, v45
	v_fmac_f32_e32 v66, v138, v46
	v_fmac_f32_e32 v67, v139, v47
	ds_read_b128 v[136:139], v105 offset:48784
	s_waitcnt lgkmcnt(11)
	v_fmac_f32_e32 v66, v140, v48
	v_fmac_f32_e32 v67, v141, v49
	v_fmac_f32_e32 v66, v142, v50
	v_fmac_f32_e32 v67, v143, v51
	ds_read_b128 v[140:143], v105 offset:48800
	s_waitcnt lgkmcnt(11)
	v_fmac_f32_e32 v66, v144, v52
	v_fmac_f32_e32 v67, v145, v53
	v_fmac_f32_e32 v66, v146, v54
	v_sub_f32_e32 v55, v55, v66
	v_sub_f32_e32 v55, v55, v67
	ds_read_b128 v[144:147], v105 offset:48816
	s_waitcnt lgkmcnt(11)
	v_mul_f32_e32 v66, v148, v0
	v_mul_f32_e32 v67, v149, v4
	v_fmac_f32_e32 v66, v150, v5
	v_fmac_f32_e32 v67, v151, v6
	ds_read_b128 v[148:151], v105 offset:48832
	s_waitcnt lgkmcnt(11)
	v_fmac_f32_e32 v66, v152, v7
	v_fmac_f32_e32 v67, v153, v8
	v_fmac_f32_e32 v66, v154, v9
	v_fmac_f32_e32 v67, v155, v10
	ds_read_b128 v[152:155], v105 offset:48896
	s_waitcnt lgkmcnt(11)
	v_fmac_f32_e32 v66, v156, v11
	v_fmac_f32_e32 v67, v157, v12
	v_fmac_f32_e32 v66, v158, v13
	v_fmac_f32_e32 v67, v159, v14
	ds_read_b128 v[156:159], v105 offset:48912
	s_waitcnt lgkmcnt(11)
	v_fmac_f32_e32 v66, v160, v15
	v_fmac_f32_e32 v67, v161, v16
	v_fmac_f32_e32 v66, v162, v17
	v_fmac_f32_e32 v67, v163, v18
	ds_read_b128 v[160:163], v105 offset:48928
	s_waitcnt lgkmcnt(11)
	v_fmac_f32_e32 v66, v164, v20
	v_fmac_f32_e32 v67, v165, v21
	v_fmac_f32_e32 v66, v166, v22
	v_fmac_f32_e32 v67, v167, v23
	ds_read_b128 v[164:167], v105 offset:48944
	s_waitcnt lgkmcnt(11)
	v_fmac_f32_e32 v66, v168, v24
	v_fmac_f32_e32 v67, v169, v25
	v_fmac_f32_e32 v66, v170, v26
	v_fmac_f32_e32 v67, v171, v27
	ds_read_b128 v[168:171], v105 offset:48960
	s_waitcnt lgkmcnt(11)
	v_fmac_f32_e32 v66, v172, v28
	v_fmac_f32_e32 v67, v173, v29
	v_fmac_f32_e32 v66, v174, v30
	v_fmac_f32_e32 v67, v175, v31
	ds_read_b128 v[172:175], v105 offset:48976
	s_waitcnt lgkmcnt(11)
	v_fmac_f32_e32 v66, v176, v32
	v_fmac_f32_e32 v67, v177, v33
	v_fmac_f32_e32 v66, v178, v34
	v_fmac_f32_e32 v67, v179, v35
	ds_read_b128 v[176:179], v105 offset:48992
	s_waitcnt lgkmcnt(11)
	v_fmac_f32_e32 v66, v180, v36
	v_fmac_f32_e32 v67, v181, v37
	v_fmac_f32_e32 v66, v182, v38
	v_fmac_f32_e32 v67, v183, v39
	ds_read_b128 v[180:183], v105 offset:49008
	s_waitcnt lgkmcnt(11)
	v_fmac_f32_e32 v66, v136, v40
	v_fmac_f32_e32 v67, v137, v41
	v_fmac_f32_e32 v66, v138, v42
	v_fmac_f32_e32 v67, v139, v43
	ds_read_b128 v[136:139], v105 offset:49024
	s_waitcnt lgkmcnt(11)
	v_fmac_f32_e32 v66, v140, v44
	v_fmac_f32_e32 v67, v141, v45
	v_fmac_f32_e32 v66, v142, v46
	v_fmac_f32_e32 v67, v143, v47
	ds_read_b128 v[140:143], v105 offset:49040
	s_waitcnt lgkmcnt(11)
	v_fmac_f32_e32 v66, v144, v48
	v_fmac_f32_e32 v67, v145, v49
	v_fmac_f32_e32 v66, v146, v50
	v_fmac_f32_e32 v67, v147, v51
	ds_read_b128 v[144:147], v105 offset:49056
	s_waitcnt lgkmcnt(11)
	v_fmac_f32_e32 v66, v148, v52
	v_fmac_f32_e32 v67, v149, v53
	v_fmac_f32_e32 v66, v150, v54
	v_fmac_f32_e32 v67, v151, v55
	v_sub_f32_e32 v56, v56, v66
	v_sub_f32_e32 v56, v56, v67
	ds_read_b128 v[148:151], v105 offset:49072
	s_waitcnt lgkmcnt(11)
	v_mul_f32_e32 v66, v152, v0
	v_mul_f32_e32 v67, v153, v4
	v_fmac_f32_e32 v66, v154, v5
	v_fmac_f32_e32 v67, v155, v6
	ds_read_b128 v[152:155], v105 offset:49088
	s_waitcnt lgkmcnt(11)
	v_fmac_f32_e32 v66, v156, v7
	v_fmac_f32_e32 v67, v157, v8
	v_fmac_f32_e32 v66, v158, v9
	v_fmac_f32_e32 v67, v159, v10
	ds_read_b128 v[156:159], v105 offset:49104
	s_waitcnt lgkmcnt(11)
	v_fmac_f32_e32 v66, v160, v11
	v_fmac_f32_e32 v67, v161, v12
	v_fmac_f32_e32 v66, v162, v13
	v_fmac_f32_e32 v67, v163, v14
	ds_read_b128 v[160:163], v105 offset:49152
	s_waitcnt lgkmcnt(11)
	v_fmac_f32_e32 v66, v164, v15
	v_fmac_f32_e32 v67, v165, v16
	v_fmac_f32_e32 v66, v166, v17
	v_fmac_f32_e32 v67, v167, v18
	ds_read_b128 v[164:167], v105 offset:49168
	s_waitcnt lgkmcnt(11)
	v_fmac_f32_e32 v66, v168, v20
	v_fmac_f32_e32 v67, v169, v21
	v_fmac_f32_e32 v66, v170, v22
	v_fmac_f32_e32 v67, v171, v23
	ds_read_b128 v[168:171], v105 offset:49184
	s_waitcnt lgkmcnt(11)
	v_fmac_f32_e32 v66, v172, v24
	v_fmac_f32_e32 v67, v173, v25
	v_fmac_f32_e32 v66, v174, v26
	v_fmac_f32_e32 v67, v175, v27
	ds_read_b128 v[172:175], v105 offset:49200
	s_waitcnt lgkmcnt(11)
	v_fmac_f32_e32 v66, v176, v28
	v_fmac_f32_e32 v67, v177, v29
	v_fmac_f32_e32 v66, v178, v30
	v_fmac_f32_e32 v67, v179, v31
	ds_read_b128 v[176:179], v105 offset:49216
	s_waitcnt lgkmcnt(11)
	v_fmac_f32_e32 v66, v180, v32
	v_fmac_f32_e32 v67, v181, v33
	v_fmac_f32_e32 v66, v182, v34
	v_fmac_f32_e32 v67, v183, v35
	ds_read_b128 v[180:183], v105 offset:49232
	s_waitcnt lgkmcnt(11)
	v_fmac_f32_e32 v66, v136, v36
	v_fmac_f32_e32 v67, v137, v37
	v_fmac_f32_e32 v66, v138, v38
	v_fmac_f32_e32 v67, v139, v39
	ds_read_b128 v[136:139], v105 offset:49248
	s_waitcnt lgkmcnt(11)
	v_fmac_f32_e32 v66, v140, v40
	v_fmac_f32_e32 v67, v141, v41
	v_fmac_f32_e32 v66, v142, v42
	v_fmac_f32_e32 v67, v143, v43
	ds_read_b128 v[140:143], v105 offset:49264
	s_waitcnt lgkmcnt(11)
	v_fmac_f32_e32 v66, v144, v44
	v_fmac_f32_e32 v67, v145, v45
	v_fmac_f32_e32 v66, v146, v46
	v_fmac_f32_e32 v67, v147, v47
	ds_read_b128 v[144:147], v105 offset:49280
	s_waitcnt lgkmcnt(11)
	v_fmac_f32_e32 v66, v148, v48
	v_fmac_f32_e32 v67, v149, v49
	v_fmac_f32_e32 v66, v150, v50
	v_fmac_f32_e32 v67, v151, v51
	ds_read_b128 v[148:151], v105 offset:49296
	s_waitcnt lgkmcnt(11)
	v_fmac_f32_e32 v66, v152, v52
	v_fmac_f32_e32 v67, v153, v53
	v_fmac_f32_e32 v66, v154, v54
	v_fmac_f32_e32 v67, v155, v55
	ds_read_b128 v[152:155], v105 offset:49312
	s_waitcnt lgkmcnt(11)
	v_fmac_f32_e32 v66, v156, v56
	v_sub_f32_e32 v57, v57, v66
	v_sub_f32_e32 v57, v57, v67
	ds_read_b128 v[156:159], v105 offset:49328
	s_waitcnt lgkmcnt(11)
	v_mul_f32_e32 v66, v160, v0
	v_mul_f32_e32 v67, v161, v4
	v_fmac_f32_e32 v66, v162, v5
	v_fmac_f32_e32 v67, v163, v6
	ds_read_b128 v[160:163], v105 offset:49344
	s_waitcnt lgkmcnt(11)
	v_fmac_f32_e32 v66, v164, v7
	v_fmac_f32_e32 v67, v165, v8
	v_fmac_f32_e32 v66, v166, v9
	v_fmac_f32_e32 v67, v167, v10
	ds_read_b128 v[164:167], v105 offset:49360
	s_waitcnt lgkmcnt(11)
	v_fmac_f32_e32 v66, v168, v11
	v_fmac_f32_e32 v67, v169, v12
	v_fmac_f32_e32 v66, v170, v13
	v_fmac_f32_e32 v67, v171, v14
	ds_read_b128 v[168:171], v105 offset:49408
	s_waitcnt lgkmcnt(11)
	v_fmac_f32_e32 v66, v172, v15
	v_fmac_f32_e32 v67, v173, v16
	v_fmac_f32_e32 v66, v174, v17
	v_fmac_f32_e32 v67, v175, v18
	ds_read_b128 v[172:175], v105 offset:49424
	s_waitcnt lgkmcnt(11)
	v_fmac_f32_e32 v66, v176, v20
	v_fmac_f32_e32 v67, v177, v21
	v_fmac_f32_e32 v66, v178, v22
	v_fmac_f32_e32 v67, v179, v23
	ds_read_b128 v[176:179], v105 offset:49440
	s_waitcnt lgkmcnt(11)
	v_fmac_f32_e32 v66, v180, v24
	v_fmac_f32_e32 v67, v181, v25
	v_fmac_f32_e32 v66, v182, v26
	v_fmac_f32_e32 v67, v183, v27
	ds_read_b128 v[180:183], v105 offset:49456
	s_waitcnt lgkmcnt(11)
	v_fmac_f32_e32 v66, v136, v28
	v_fmac_f32_e32 v67, v137, v29
	v_fmac_f32_e32 v66, v138, v30
	v_fmac_f32_e32 v67, v139, v31
	ds_read_b128 v[136:139], v105 offset:49472
	s_waitcnt lgkmcnt(11)
	v_fmac_f32_e32 v66, v140, v32
	v_fmac_f32_e32 v67, v141, v33
	v_fmac_f32_e32 v66, v142, v34
	v_fmac_f32_e32 v67, v143, v35
	ds_read_b128 v[140:143], v105 offset:49488
	s_waitcnt lgkmcnt(11)
	v_fmac_f32_e32 v66, v144, v36
	v_fmac_f32_e32 v67, v145, v37
	v_fmac_f32_e32 v66, v146, v38
	v_fmac_f32_e32 v67, v147, v39
	ds_read_b128 v[144:147], v105 offset:49504
	s_waitcnt lgkmcnt(11)
	v_fmac_f32_e32 v66, v148, v40
	v_fmac_f32_e32 v67, v149, v41
	v_fmac_f32_e32 v66, v150, v42
	v_fmac_f32_e32 v67, v151, v43
	ds_read_b128 v[148:151], v105 offset:49520
	s_waitcnt lgkmcnt(11)
	v_fmac_f32_e32 v66, v152, v44
	v_fmac_f32_e32 v67, v153, v45
	v_fmac_f32_e32 v66, v154, v46
	v_fmac_f32_e32 v67, v155, v47
	ds_read_b128 v[152:155], v105 offset:49536
	s_waitcnt lgkmcnt(11)
	v_fmac_f32_e32 v66, v156, v48
	v_fmac_f32_e32 v67, v157, v49
	v_fmac_f32_e32 v66, v158, v50
	v_fmac_f32_e32 v67, v159, v51
	ds_read_b128 v[156:159], v105 offset:49552
	s_waitcnt lgkmcnt(11)
	v_fmac_f32_e32 v66, v160, v52
	v_fmac_f32_e32 v67, v161, v53
	v_fmac_f32_e32 v66, v162, v54
	v_fmac_f32_e32 v67, v163, v55
	ds_read_b128 v[160:163], v105 offset:49568
	s_waitcnt lgkmcnt(11)
	v_fmac_f32_e32 v66, v164, v56
	v_fmac_f32_e32 v67, v165, v57
	v_sub_f32_e32 v58, v58, v66
	v_sub_f32_e32 v58, v58, v67
	ds_read_b128 v[164:167], v105 offset:49584
	s_waitcnt lgkmcnt(11)
	v_mul_f32_e32 v66, v168, v0
	v_mul_f32_e32 v67, v169, v4
	v_fmac_f32_e32 v66, v170, v5
	v_fmac_f32_e32 v67, v171, v6
	ds_read_b128 v[168:171], v105 offset:49600
	s_waitcnt lgkmcnt(11)
	v_fmac_f32_e32 v66, v172, v7
	v_fmac_f32_e32 v67, v173, v8
	v_fmac_f32_e32 v66, v174, v9
	v_fmac_f32_e32 v67, v175, v10
	ds_read_b128 v[172:175], v105 offset:49616
	s_waitcnt lgkmcnt(11)
	v_fmac_f32_e32 v66, v176, v11
	v_fmac_f32_e32 v67, v177, v12
	v_fmac_f32_e32 v66, v178, v13
	v_fmac_f32_e32 v67, v179, v14
	ds_read_b128 v[176:179], v105 offset:49664
	s_waitcnt lgkmcnt(11)
	v_fmac_f32_e32 v66, v180, v15
	v_fmac_f32_e32 v67, v181, v16
	v_fmac_f32_e32 v66, v182, v17
	v_fmac_f32_e32 v67, v183, v18
	ds_read_b128 v[180:183], v105 offset:49680
	s_waitcnt lgkmcnt(11)
	v_fmac_f32_e32 v66, v136, v20
	v_fmac_f32_e32 v67, v137, v21
	v_fmac_f32_e32 v66, v138, v22
	v_fmac_f32_e32 v67, v139, v23
	ds_read_b128 v[136:139], v105 offset:49696
	s_waitcnt lgkmcnt(11)
	v_fmac_f32_e32 v66, v140, v24
	v_fmac_f32_e32 v67, v141, v25
	v_fmac_f32_e32 v66, v142, v26
	v_fmac_f32_e32 v67, v143, v27
	ds_read_b128 v[140:143], v105 offset:49712
	s_waitcnt lgkmcnt(11)
	v_fmac_f32_e32 v66, v144, v28
	v_fmac_f32_e32 v67, v145, v29
	v_fmac_f32_e32 v66, v146, v30
	v_fmac_f32_e32 v67, v147, v31
	ds_read_b128 v[144:147], v105 offset:49728
	s_waitcnt lgkmcnt(11)
	v_fmac_f32_e32 v66, v148, v32
	v_fmac_f32_e32 v67, v149, v33
	v_fmac_f32_e32 v66, v150, v34
	v_fmac_f32_e32 v67, v151, v35
	ds_read_b128 v[148:151], v105 offset:49744
	s_waitcnt lgkmcnt(11)
	v_fmac_f32_e32 v66, v152, v36
	v_fmac_f32_e32 v67, v153, v37
	v_fmac_f32_e32 v66, v154, v38
	v_fmac_f32_e32 v67, v155, v39
	ds_read_b128 v[152:155], v105 offset:49760
	s_waitcnt lgkmcnt(11)
	v_fmac_f32_e32 v66, v156, v40
	v_fmac_f32_e32 v67, v157, v41
	v_fmac_f32_e32 v66, v158, v42
	v_fmac_f32_e32 v67, v159, v43
	ds_read_b128 v[156:159], v105 offset:49776
	s_waitcnt lgkmcnt(11)
	v_fmac_f32_e32 v66, v160, v44
	v_fmac_f32_e32 v67, v161, v45
	v_fmac_f32_e32 v66, v162, v46
	v_fmac_f32_e32 v67, v163, v47
	ds_read_b128 v[160:163], v105 offset:49792
	s_waitcnt lgkmcnt(11)
	v_fmac_f32_e32 v66, v164, v48
	v_fmac_f32_e32 v67, v165, v49
	v_fmac_f32_e32 v66, v166, v50
	v_fmac_f32_e32 v67, v167, v51
	ds_read_b128 v[164:167], v105 offset:49808
	s_waitcnt lgkmcnt(11)
	v_fmac_f32_e32 v66, v168, v52
	v_fmac_f32_e32 v67, v169, v53
	v_fmac_f32_e32 v66, v170, v54
	v_fmac_f32_e32 v67, v171, v55
	ds_read_b128 v[168:171], v105 offset:49824
	s_waitcnt lgkmcnt(11)
	v_fmac_f32_e32 v66, v172, v56
	v_fmac_f32_e32 v67, v173, v57
	v_fmac_f32_e32 v66, v174, v58
	v_sub_f32_e32 v59, v59, v66
	v_sub_f32_e32 v59, v59, v67
	ds_read_b128 v[172:175], v105 offset:49840
	s_waitcnt lgkmcnt(11)
	v_mul_f32_e32 v66, v176, v0
	v_mul_f32_e32 v67, v177, v4
	v_fmac_f32_e32 v66, v178, v5
	v_fmac_f32_e32 v67, v179, v6
	ds_read_b128 v[176:179], v105 offset:49856
	s_waitcnt lgkmcnt(11)
	v_fmac_f32_e32 v66, v180, v7
	v_fmac_f32_e32 v67, v181, v8
	v_fmac_f32_e32 v66, v182, v9
	v_fmac_f32_e32 v67, v183, v10
	ds_read_b128 v[180:183], v105 offset:49872
	s_waitcnt lgkmcnt(11)
	v_fmac_f32_e32 v66, v136, v11
	v_fmac_f32_e32 v67, v137, v12
	v_fmac_f32_e32 v66, v138, v13
	v_fmac_f32_e32 v67, v139, v14
	ds_read_b128 v[136:139], v105 offset:49920
	s_waitcnt lgkmcnt(11)
	v_fmac_f32_e32 v66, v140, v15
	v_fmac_f32_e32 v67, v141, v16
	v_fmac_f32_e32 v66, v142, v17
	v_fmac_f32_e32 v67, v143, v18
	ds_read_b128 v[140:143], v105 offset:49936
	s_waitcnt lgkmcnt(11)
	v_fmac_f32_e32 v66, v144, v20
	v_fmac_f32_e32 v67, v145, v21
	v_fmac_f32_e32 v66, v146, v22
	v_fmac_f32_e32 v67, v147, v23
	ds_read_b128 v[144:147], v105 offset:49952
	s_waitcnt lgkmcnt(11)
	v_fmac_f32_e32 v66, v148, v24
	v_fmac_f32_e32 v67, v149, v25
	v_fmac_f32_e32 v66, v150, v26
	v_fmac_f32_e32 v67, v151, v27
	ds_read_b128 v[148:151], v105 offset:49968
	s_waitcnt lgkmcnt(11)
	v_fmac_f32_e32 v66, v152, v28
	v_fmac_f32_e32 v67, v153, v29
	v_fmac_f32_e32 v66, v154, v30
	v_fmac_f32_e32 v67, v155, v31
	ds_read_b128 v[152:155], v105 offset:49984
	s_waitcnt lgkmcnt(11)
	v_fmac_f32_e32 v66, v156, v32
	v_fmac_f32_e32 v67, v157, v33
	v_fmac_f32_e32 v66, v158, v34
	v_fmac_f32_e32 v67, v159, v35
	ds_read_b128 v[156:159], v105 offset:50000
	s_waitcnt lgkmcnt(11)
	v_fmac_f32_e32 v66, v160, v36
	v_fmac_f32_e32 v67, v161, v37
	v_fmac_f32_e32 v66, v162, v38
	v_fmac_f32_e32 v67, v163, v39
	ds_read_b128 v[160:163], v105 offset:50016
	s_waitcnt lgkmcnt(11)
	v_fmac_f32_e32 v66, v164, v40
	v_fmac_f32_e32 v67, v165, v41
	v_fmac_f32_e32 v66, v166, v42
	v_fmac_f32_e32 v67, v167, v43
	ds_read_b128 v[164:167], v105 offset:50032
	s_waitcnt lgkmcnt(11)
	v_fmac_f32_e32 v66, v168, v44
	v_fmac_f32_e32 v67, v169, v45
	v_fmac_f32_e32 v66, v170, v46
	v_fmac_f32_e32 v67, v171, v47
	ds_read_b128 v[168:171], v105 offset:50048
	s_waitcnt lgkmcnt(11)
	v_fmac_f32_e32 v66, v172, v48
	v_fmac_f32_e32 v67, v173, v49
	v_fmac_f32_e32 v66, v174, v50
	v_fmac_f32_e32 v67, v175, v51
	ds_read_b128 v[172:175], v105 offset:50064
	s_waitcnt lgkmcnt(11)
	v_fmac_f32_e32 v66, v176, v52
	v_fmac_f32_e32 v67, v177, v53
	v_fmac_f32_e32 v66, v178, v54
	v_fmac_f32_e32 v67, v179, v55
	ds_read_b128 v[176:179], v105 offset:50080
	s_waitcnt lgkmcnt(11)
	v_fmac_f32_e32 v66, v180, v56
	v_fmac_f32_e32 v67, v181, v57
	v_fmac_f32_e32 v66, v182, v58
	v_fmac_f32_e32 v67, v183, v59
	v_sub_f32_e32 v60, v60, v66
	v_sub_f32_e32 v60, v60, v67
	ds_read_b128 v[180:183], v105 offset:50096
	s_waitcnt lgkmcnt(11)
	v_mul_f32_e32 v66, v136, v0
	v_mul_f32_e32 v67, v137, v4
	v_fmac_f32_e32 v66, v138, v5
	v_fmac_f32_e32 v67, v139, v6
	ds_read_b128 v[136:139], v105 offset:50112
	s_waitcnt lgkmcnt(11)
	v_fmac_f32_e32 v66, v140, v7
	v_fmac_f32_e32 v67, v141, v8
	v_fmac_f32_e32 v66, v142, v9
	v_fmac_f32_e32 v67, v143, v10
	ds_read_b128 v[140:143], v105 offset:50128
	s_waitcnt lgkmcnt(11)
	v_fmac_f32_e32 v66, v144, v11
	v_fmac_f32_e32 v67, v145, v12
	v_fmac_f32_e32 v66, v146, v13
	v_fmac_f32_e32 v67, v147, v14
	ds_read_b128 v[144:147], v105 offset:50144
	s_waitcnt lgkmcnt(11)
	v_fmac_f32_e32 v66, v148, v15
	v_fmac_f32_e32 v67, v149, v16
	v_fmac_f32_e32 v66, v150, v17
	v_fmac_f32_e32 v67, v151, v18
	ds_read_b128 v[148:151], v105 offset:50176
	s_waitcnt lgkmcnt(11)
	v_fmac_f32_e32 v66, v152, v20
	v_fmac_f32_e32 v67, v153, v21
	v_fmac_f32_e32 v66, v154, v22
	v_fmac_f32_e32 v67, v155, v23
	ds_read_b128 v[152:155], v105 offset:50192
	s_waitcnt lgkmcnt(11)
	v_fmac_f32_e32 v66, v156, v24
	v_fmac_f32_e32 v67, v157, v25
	v_fmac_f32_e32 v66, v158, v26
	v_fmac_f32_e32 v67, v159, v27
	ds_read_b128 v[156:159], v105 offset:50208
	s_waitcnt lgkmcnt(11)
	v_fmac_f32_e32 v66, v160, v28
	v_fmac_f32_e32 v67, v161, v29
	v_fmac_f32_e32 v66, v162, v30
	v_fmac_f32_e32 v67, v163, v31
	ds_read_b128 v[160:163], v105 offset:50224
	s_waitcnt lgkmcnt(11)
	v_fmac_f32_e32 v66, v164, v32
	v_fmac_f32_e32 v67, v165, v33
	v_fmac_f32_e32 v66, v166, v34
	v_fmac_f32_e32 v67, v167, v35
	ds_read_b128 v[164:167], v105 offset:50240
	s_waitcnt lgkmcnt(11)
	v_fmac_f32_e32 v66, v168, v36
	v_fmac_f32_e32 v67, v169, v37
	v_fmac_f32_e32 v66, v170, v38
	v_fmac_f32_e32 v67, v171, v39
	ds_read_b128 v[168:171], v105 offset:50256
	s_waitcnt lgkmcnt(11)
	v_fmac_f32_e32 v66, v172, v40
	v_fmac_f32_e32 v67, v173, v41
	v_fmac_f32_e32 v66, v174, v42
	v_fmac_f32_e32 v67, v175, v43
	ds_read_b128 v[172:175], v105 offset:50272
	s_waitcnt lgkmcnt(11)
	v_fmac_f32_e32 v66, v176, v44
	v_fmac_f32_e32 v67, v177, v45
	v_fmac_f32_e32 v66, v178, v46
	v_fmac_f32_e32 v67, v179, v47
	ds_read_b128 v[176:179], v105 offset:50288
	s_waitcnt lgkmcnt(11)
	v_fmac_f32_e32 v66, v180, v48
	v_fmac_f32_e32 v67, v181, v49
	v_fmac_f32_e32 v66, v182, v50
	v_fmac_f32_e32 v67, v183, v51
	ds_read_b128 v[180:183], v105 offset:50304
	s_waitcnt lgkmcnt(11)
	v_fmac_f32_e32 v66, v136, v52
	v_fmac_f32_e32 v67, v137, v53
	v_fmac_f32_e32 v66, v138, v54
	v_fmac_f32_e32 v67, v139, v55
	ds_read_b128 v[136:139], v105 offset:50320
	s_waitcnt lgkmcnt(11)
	v_fmac_f32_e32 v66, v140, v56
	v_fmac_f32_e32 v67, v141, v57
	v_fmac_f32_e32 v66, v142, v58
	v_fmac_f32_e32 v67, v143, v59
	ds_read_b128 v[140:143], v105 offset:50336
	s_waitcnt lgkmcnt(11)
	v_fmac_f32_e32 v66, v144, v60
	v_sub_f32_e32 v61, v61, v66
	v_sub_f32_e32 v61, v61, v67
	ds_read_b128 v[144:147], v105 offset:50352
	s_waitcnt lgkmcnt(11)
	v_mul_f32_e32 v66, v148, v0
	v_mul_f32_e32 v67, v149, v4
	v_fmac_f32_e32 v66, v150, v5
	v_fmac_f32_e32 v67, v151, v6
	ds_read_b128 v[148:151], v105 offset:50368
	s_waitcnt lgkmcnt(11)
	v_fmac_f32_e32 v66, v152, v7
	v_fmac_f32_e32 v67, v153, v8
	v_fmac_f32_e32 v66, v154, v9
	v_fmac_f32_e32 v67, v155, v10
	ds_read_b128 v[152:155], v105 offset:50384
	s_waitcnt lgkmcnt(11)
	v_fmac_f32_e32 v66, v156, v11
	v_fmac_f32_e32 v67, v157, v12
	v_fmac_f32_e32 v66, v158, v13
	v_fmac_f32_e32 v67, v159, v14
	ds_read_b128 v[156:159], v105 offset:50400
	s_waitcnt lgkmcnt(11)
	v_fmac_f32_e32 v66, v160, v15
	v_fmac_f32_e32 v67, v161, v16
	v_fmac_f32_e32 v66, v162, v17
	v_fmac_f32_e32 v67, v163, v18
	ds_read_b128 v[160:163], v105 offset:50432
	s_waitcnt lgkmcnt(11)
	v_fmac_f32_e32 v66, v164, v20
	v_fmac_f32_e32 v67, v165, v21
	v_fmac_f32_e32 v66, v166, v22
	v_fmac_f32_e32 v67, v167, v23
	ds_read_b128 v[164:167], v105 offset:50448
	s_waitcnt lgkmcnt(11)
	v_fmac_f32_e32 v66, v168, v24
	v_fmac_f32_e32 v67, v169, v25
	v_fmac_f32_e32 v66, v170, v26
	v_fmac_f32_e32 v67, v171, v27
	ds_read_b128 v[168:171], v105 offset:50464
	s_waitcnt lgkmcnt(11)
	v_fmac_f32_e32 v66, v172, v28
	v_fmac_f32_e32 v67, v173, v29
	v_fmac_f32_e32 v66, v174, v30
	v_fmac_f32_e32 v67, v175, v31
	ds_read_b128 v[172:175], v105 offset:50480
	s_waitcnt lgkmcnt(11)
	v_fmac_f32_e32 v66, v176, v32
	v_fmac_f32_e32 v67, v177, v33
	v_fmac_f32_e32 v66, v178, v34
	v_fmac_f32_e32 v67, v179, v35
	ds_read_b128 v[176:179], v105 offset:50496
	s_waitcnt lgkmcnt(11)
	v_fmac_f32_e32 v66, v180, v36
	v_fmac_f32_e32 v67, v181, v37
	v_fmac_f32_e32 v66, v182, v38
	v_fmac_f32_e32 v67, v183, v39
	ds_read_b128 v[180:183], v105 offset:50512
	s_waitcnt lgkmcnt(11)
	v_fmac_f32_e32 v66, v136, v40
	v_fmac_f32_e32 v67, v137, v41
	v_fmac_f32_e32 v66, v138, v42
	v_fmac_f32_e32 v67, v139, v43
	ds_read_b128 v[136:139], v105 offset:50528
	s_waitcnt lgkmcnt(11)
	v_fmac_f32_e32 v66, v140, v44
	v_fmac_f32_e32 v67, v141, v45
	v_fmac_f32_e32 v66, v142, v46
	v_fmac_f32_e32 v67, v143, v47
	ds_read_b128 v[140:143], v105 offset:50544
	s_waitcnt lgkmcnt(11)
	v_fmac_f32_e32 v66, v144, v48
	v_fmac_f32_e32 v67, v145, v49
	v_fmac_f32_e32 v66, v146, v50
	v_fmac_f32_e32 v67, v147, v51
	ds_read_b128 v[144:147], v105 offset:50560
	s_waitcnt lgkmcnt(11)
	v_fmac_f32_e32 v66, v148, v52
	v_fmac_f32_e32 v67, v149, v53
	v_fmac_f32_e32 v66, v150, v54
	v_fmac_f32_e32 v67, v151, v55
	ds_read_b128 v[148:151], v105 offset:50576
	s_waitcnt lgkmcnt(11)
	v_fmac_f32_e32 v66, v152, v56
	v_fmac_f32_e32 v67, v153, v57
	v_fmac_f32_e32 v66, v154, v58
	v_fmac_f32_e32 v67, v155, v59
	ds_read_b128 v[152:155], v105 offset:50592
	s_waitcnt lgkmcnt(11)
	v_fmac_f32_e32 v66, v156, v60
	v_fmac_f32_e32 v67, v157, v61
	v_sub_f32_e32 v62, v62, v66
	v_sub_f32_e32 v62, v62, v67
	ds_read_b128 v[156:159], v105 offset:50608
	s_waitcnt lgkmcnt(11)
	v_mul_f32_e32 v66, v160, v0
	v_mul_f32_e32 v67, v161, v4
	v_fmac_f32_e32 v66, v162, v5
	v_fmac_f32_e32 v67, v163, v6
	ds_read_b128 v[160:163], v105 offset:50624
	s_waitcnt lgkmcnt(11)
	v_fmac_f32_e32 v66, v164, v7
	v_fmac_f32_e32 v67, v165, v8
	v_fmac_f32_e32 v66, v166, v9
	v_fmac_f32_e32 v67, v167, v10
	ds_read_b128 v[164:167], v105 offset:50640
	s_waitcnt lgkmcnt(11)
	v_fmac_f32_e32 v66, v168, v11
	v_fmac_f32_e32 v67, v169, v12
	v_fmac_f32_e32 v66, v170, v13
	v_fmac_f32_e32 v67, v171, v14
	ds_read_b128 v[168:171], v105 offset:50656
	s_waitcnt lgkmcnt(11)
	v_fmac_f32_e32 v66, v172, v15
	v_fmac_f32_e32 v67, v173, v16
	v_fmac_f32_e32 v66, v174, v17
	v_fmac_f32_e32 v67, v175, v18
	ds_read_b128 v[172:175], v105 offset:50688
	s_waitcnt lgkmcnt(11)
	v_fmac_f32_e32 v66, v176, v20
	v_fmac_f32_e32 v67, v177, v21
	v_fmac_f32_e32 v66, v178, v22
	v_fmac_f32_e32 v67, v179, v23
	ds_read_b128 v[176:179], v105 offset:50704
	s_waitcnt lgkmcnt(11)
	v_fmac_f32_e32 v66, v180, v24
	v_fmac_f32_e32 v67, v181, v25
	v_fmac_f32_e32 v66, v182, v26
	v_fmac_f32_e32 v67, v183, v27
	ds_read_b128 v[180:183], v105 offset:50720
	s_waitcnt lgkmcnt(11)
	v_fmac_f32_e32 v66, v136, v28
	v_fmac_f32_e32 v67, v137, v29
	v_fmac_f32_e32 v66, v138, v30
	v_fmac_f32_e32 v67, v139, v31
	ds_read_b128 v[136:139], v105 offset:50736
	s_waitcnt lgkmcnt(11)
	v_fmac_f32_e32 v66, v140, v32
	v_fmac_f32_e32 v67, v141, v33
	v_fmac_f32_e32 v66, v142, v34
	v_fmac_f32_e32 v67, v143, v35
	ds_read_b128 v[140:143], v105 offset:50752
	s_waitcnt lgkmcnt(11)
	v_fmac_f32_e32 v66, v144, v36
	v_fmac_f32_e32 v67, v145, v37
	v_fmac_f32_e32 v66, v146, v38
	v_fmac_f32_e32 v67, v147, v39
	ds_read_b128 v[144:147], v105 offset:50768
	s_waitcnt lgkmcnt(11)
	v_fmac_f32_e32 v66, v148, v40
	v_fmac_f32_e32 v67, v149, v41
	v_fmac_f32_e32 v66, v150, v42
	v_fmac_f32_e32 v67, v151, v43
	ds_read_b128 v[148:151], v105 offset:50784
	s_waitcnt lgkmcnt(11)
	v_fmac_f32_e32 v66, v152, v44
	v_fmac_f32_e32 v67, v153, v45
	v_fmac_f32_e32 v66, v154, v46
	v_fmac_f32_e32 v67, v155, v47
	ds_read_b128 v[152:155], v105 offset:50800
	s_waitcnt lgkmcnt(11)
	v_fmac_f32_e32 v66, v156, v48
	v_fmac_f32_e32 v67, v157, v49
	v_fmac_f32_e32 v66, v158, v50
	v_fmac_f32_e32 v67, v159, v51
	ds_read_b128 v[156:159], v105 offset:50816
	s_waitcnt lgkmcnt(11)
	v_fmac_f32_e32 v66, v160, v52
	v_fmac_f32_e32 v67, v161, v53
	v_fmac_f32_e32 v66, v162, v54
	v_fmac_f32_e32 v67, v163, v55
	ds_read_b128 v[160:163], v105 offset:50832
	s_waitcnt lgkmcnt(11)
	v_fmac_f32_e32 v66, v164, v56
	v_fmac_f32_e32 v67, v165, v57
	v_fmac_f32_e32 v66, v166, v58
	v_fmac_f32_e32 v67, v167, v59
	ds_read_b128 v[164:167], v105 offset:50848
	s_waitcnt lgkmcnt(11)
	v_fmac_f32_e32 v66, v168, v60
	v_fmac_f32_e32 v67, v169, v61
	v_fmac_f32_e32 v66, v170, v62
	v_sub_f32_e32 v63, v63, v66
	v_sub_f32_e32 v63, v63, v67
	ds_read_b128 v[168:171], v105 offset:50864
	s_waitcnt lgkmcnt(11)
	v_mul_f32_e32 v66, v172, v0
	v_mul_f32_e32 v67, v173, v4
	v_fmac_f32_e32 v66, v174, v5
	v_fmac_f32_e32 v67, v175, v6
	ds_read_b128 v[172:175], v105 offset:50880
	s_waitcnt lgkmcnt(11)
	v_fmac_f32_e32 v66, v176, v7
	v_fmac_f32_e32 v67, v177, v8
	v_fmac_f32_e32 v66, v178, v9
	v_fmac_f32_e32 v67, v179, v10
	ds_read_b128 v[176:179], v105 offset:50896
	s_waitcnt lgkmcnt(11)
	v_fmac_f32_e32 v66, v180, v11
	v_fmac_f32_e32 v67, v181, v12
	v_fmac_f32_e32 v66, v182, v13
	v_fmac_f32_e32 v67, v183, v14
	ds_read_b128 v[180:183], v105 offset:50912
	s_waitcnt lgkmcnt(11)
	v_fmac_f32_e32 v66, v136, v15
	v_fmac_f32_e32 v67, v137, v16
	v_fmac_f32_e32 v66, v138, v17
	v_fmac_f32_e32 v67, v139, v18
	ds_read_b128 v[136:139], v105 offset:50944
	s_waitcnt lgkmcnt(11)
	v_fmac_f32_e32 v66, v140, v20
	v_fmac_f32_e32 v67, v141, v21
	v_fmac_f32_e32 v66, v142, v22
	v_fmac_f32_e32 v67, v143, v23
	ds_read_b128 v[140:143], v105 offset:50960
	s_waitcnt lgkmcnt(11)
	v_fmac_f32_e32 v66, v144, v24
	v_fmac_f32_e32 v67, v145, v25
	v_fmac_f32_e32 v66, v146, v26
	v_fmac_f32_e32 v67, v147, v27
	ds_read_b128 v[144:147], v105 offset:50976
	s_waitcnt lgkmcnt(11)
	v_fmac_f32_e32 v66, v148, v28
	v_fmac_f32_e32 v67, v149, v29
	v_fmac_f32_e32 v66, v150, v30
	v_fmac_f32_e32 v67, v151, v31
	ds_read_b128 v[148:151], v105 offset:50992
	s_waitcnt lgkmcnt(11)
	v_fmac_f32_e32 v66, v152, v32
	v_fmac_f32_e32 v67, v153, v33
	v_fmac_f32_e32 v66, v154, v34
	v_fmac_f32_e32 v67, v155, v35
	ds_read_b128 v[152:155], v105 offset:51008
	s_waitcnt lgkmcnt(11)
	v_fmac_f32_e32 v66, v156, v36
	v_fmac_f32_e32 v67, v157, v37
	v_fmac_f32_e32 v66, v158, v38
	v_fmac_f32_e32 v67, v159, v39
	ds_read_b128 v[156:159], v105 offset:51024
	s_waitcnt lgkmcnt(11)
	v_fmac_f32_e32 v66, v160, v40
	v_fmac_f32_e32 v67, v161, v41
	v_fmac_f32_e32 v66, v162, v42
	v_fmac_f32_e32 v67, v163, v43
	ds_read_b128 v[160:163], v105 offset:51040
	s_waitcnt lgkmcnt(11)
	v_fmac_f32_e32 v66, v164, v44
	v_fmac_f32_e32 v67, v165, v45
	v_fmac_f32_e32 v66, v166, v46
	v_fmac_f32_e32 v67, v167, v47
	ds_read_b128 v[164:167], v105 offset:51056
	s_waitcnt lgkmcnt(11)
	v_fmac_f32_e32 v66, v168, v48
	v_fmac_f32_e32 v67, v169, v49
	v_fmac_f32_e32 v66, v170, v50
	v_fmac_f32_e32 v67, v171, v51
	ds_read_b128 v[168:171], v105 offset:51072
	s_waitcnt lgkmcnt(11)
	v_fmac_f32_e32 v66, v172, v52
	v_fmac_f32_e32 v67, v173, v53
	v_fmac_f32_e32 v66, v174, v54
	v_fmac_f32_e32 v67, v175, v55
	ds_read_b128 v[172:175], v105 offset:51088
	s_waitcnt lgkmcnt(11)
	v_fmac_f32_e32 v66, v176, v56
	v_fmac_f32_e32 v67, v177, v57
	v_fmac_f32_e32 v66, v178, v58
	v_fmac_f32_e32 v67, v179, v59
	ds_read_b128 v[176:179], v105 offset:51104
	s_waitcnt lgkmcnt(11)
	v_fmac_f32_e32 v66, v180, v60
	v_fmac_f32_e32 v67, v181, v61
	v_fmac_f32_e32 v66, v182, v62
	v_fmac_f32_e32 v67, v183, v63
	v_sub_f32_e32 v64, v64, v66
	v_sub_f32_e32 v64, v64, v67
	ds_read_b128 v[180:183], v105 offset:51120
	s_waitcnt lgkmcnt(11)
	v_mul_f32_e32 v66, v136, v0
	v_mul_f32_e32 v67, v137, v4
	v_fmac_f32_e32 v66, v138, v5
	v_fmac_f32_e32 v67, v139, v6
	ds_read_b128 v[136:139], v105 offset:51136
	s_waitcnt lgkmcnt(11)
	v_fmac_f32_e32 v66, v140, v7
	v_fmac_f32_e32 v67, v141, v8
	v_fmac_f32_e32 v66, v142, v9
	v_fmac_f32_e32 v67, v143, v10
	ds_read_b128 v[140:143], v105 offset:51152
	s_waitcnt lgkmcnt(11)
	v_fmac_f32_e32 v66, v144, v11
	v_fmac_f32_e32 v67, v145, v12
	v_fmac_f32_e32 v66, v146, v13
	v_fmac_f32_e32 v67, v147, v14
	ds_read_b128 v[144:147], v105 offset:51168
	s_waitcnt lgkmcnt(11)
	v_fmac_f32_e32 v66, v148, v15
	v_fmac_f32_e32 v67, v149, v16
	v_fmac_f32_e32 v66, v150, v17
	v_fmac_f32_e32 v67, v151, v18
	ds_read_b128 v[148:151], v105 offset:51184
	s_waitcnt lgkmcnt(11)
	v_fmac_f32_e32 v66, v152, v20
	v_fmac_f32_e32 v67, v153, v21
	v_fmac_f32_e32 v66, v154, v22
	v_fmac_f32_e32 v67, v155, v23
	ds_read_b128 v[152:155], v105 offset:51200
	s_waitcnt lgkmcnt(11)
	v_fmac_f32_e32 v66, v156, v24
	v_fmac_f32_e32 v67, v157, v25
	v_fmac_f32_e32 v66, v158, v26
	v_fmac_f32_e32 v67, v159, v27
	ds_read_b128 v[156:159], v105 offset:51216
	s_waitcnt lgkmcnt(11)
	v_fmac_f32_e32 v66, v160, v28
	v_fmac_f32_e32 v67, v161, v29
	v_fmac_f32_e32 v66, v162, v30
	v_fmac_f32_e32 v67, v163, v31
	ds_read_b128 v[160:163], v105 offset:51232
	s_waitcnt lgkmcnt(11)
	v_fmac_f32_e32 v66, v164, v32
	v_fmac_f32_e32 v67, v165, v33
	v_fmac_f32_e32 v66, v166, v34
	v_fmac_f32_e32 v67, v167, v35
	ds_read_b128 v[164:167], v105 offset:51248
	s_waitcnt lgkmcnt(11)
	v_fmac_f32_e32 v66, v168, v36
	v_fmac_f32_e32 v67, v169, v37
	v_fmac_f32_e32 v66, v170, v38
	v_fmac_f32_e32 v67, v171, v39
	ds_read_b128 v[168:171], v105 offset:51264
	s_waitcnt lgkmcnt(11)
	v_fmac_f32_e32 v66, v172, v40
	v_fmac_f32_e32 v67, v173, v41
	v_fmac_f32_e32 v66, v174, v42
	v_fmac_f32_e32 v67, v175, v43
	ds_read_b128 v[172:175], v105 offset:51280
	s_waitcnt lgkmcnt(11)
	v_fmac_f32_e32 v66, v176, v44
	v_fmac_f32_e32 v67, v177, v45
	v_fmac_f32_e32 v66, v178, v46
	v_fmac_f32_e32 v67, v179, v47
	ds_read_b128 v[176:179], v105 offset:51296
	s_waitcnt lgkmcnt(11)
	v_fmac_f32_e32 v66, v180, v48
	v_fmac_f32_e32 v67, v181, v49
	v_fmac_f32_e32 v66, v182, v50
	v_fmac_f32_e32 v67, v183, v51
	ds_read_b128 v[180:183], v105 offset:51312
	s_waitcnt lgkmcnt(11)
	v_fmac_f32_e32 v66, v136, v52
	v_fmac_f32_e32 v67, v137, v53
	v_fmac_f32_e32 v66, v138, v54
	v_fmac_f32_e32 v67, v139, v55
	ds_read_b128 v[136:139], v105 offset:51328
	s_waitcnt lgkmcnt(11)
	v_fmac_f32_e32 v66, v140, v56
	v_fmac_f32_e32 v67, v141, v57
	v_fmac_f32_e32 v66, v142, v58
	v_fmac_f32_e32 v67, v143, v59
	ds_read_b128 v[140:143], v105 offset:51344
	s_waitcnt lgkmcnt(11)
	v_fmac_f32_e32 v66, v144, v60
	v_fmac_f32_e32 v67, v145, v61
	v_fmac_f32_e32 v66, v146, v62
	v_fmac_f32_e32 v67, v147, v63
	ds_read_b128 v[144:147], v105 offset:51360
	s_waitcnt lgkmcnt(11)
	v_fmac_f32_e32 v66, v148, v64
	v_sub_f32_e32 v65, v65, v66
	v_sub_f32_e32 v65, v65, v67
	ds_read_b128 v[148:151], v105 offset:51376
	s_waitcnt lgkmcnt(11)
	v_mul_f32_e32 v66, v152, v0
	v_mul_f32_e32 v67, v153, v4
	v_fmac_f32_e32 v66, v154, v5
	v_fmac_f32_e32 v67, v155, v6
	ds_read_b128 v[152:155], v105 offset:51392
	s_waitcnt lgkmcnt(11)
	v_fmac_f32_e32 v66, v156, v7
	v_fmac_f32_e32 v67, v157, v8
	v_fmac_f32_e32 v66, v158, v9
	v_fmac_f32_e32 v67, v159, v10
	ds_read_b128 v[156:159], v105 offset:51408
	s_waitcnt lgkmcnt(11)
	v_fmac_f32_e32 v66, v160, v11
	v_fmac_f32_e32 v67, v161, v12
	v_fmac_f32_e32 v66, v162, v13
	v_fmac_f32_e32 v67, v163, v14
	ds_read_b128 v[160:163], v105 offset:51424
	s_waitcnt lgkmcnt(11)
	v_fmac_f32_e32 v66, v164, v15
	v_fmac_f32_e32 v67, v165, v16
	v_fmac_f32_e32 v66, v166, v17
	v_fmac_f32_e32 v67, v167, v18
	ds_read_b128 v[164:167], v105 offset:51440
	s_waitcnt lgkmcnt(11)
	v_fmac_f32_e32 v66, v168, v20
	v_fmac_f32_e32 v67, v169, v21
	v_fmac_f32_e32 v66, v170, v22
	v_fmac_f32_e32 v67, v171, v23
	ds_read_b128 v[168:171], v105 offset:51456
	s_waitcnt lgkmcnt(11)
	v_fmac_f32_e32 v66, v172, v24
	v_fmac_f32_e32 v67, v173, v25
	v_fmac_f32_e32 v66, v174, v26
	v_fmac_f32_e32 v67, v175, v27
	ds_read_b128 v[172:175], v105 offset:51472
	s_waitcnt lgkmcnt(11)
	v_fmac_f32_e32 v66, v176, v28
	v_fmac_f32_e32 v67, v177, v29
	v_fmac_f32_e32 v66, v178, v30
	v_fmac_f32_e32 v67, v179, v31
	ds_read_b128 v[176:179], v105 offset:51488
	s_waitcnt lgkmcnt(11)
	v_fmac_f32_e32 v66, v180, v32
	v_fmac_f32_e32 v67, v181, v33
	v_fmac_f32_e32 v66, v182, v34
	v_fmac_f32_e32 v67, v183, v35
	ds_read_b128 v[180:183], v105 offset:51504
	s_waitcnt lgkmcnt(11)
	v_fmac_f32_e32 v66, v136, v36
	v_fmac_f32_e32 v67, v137, v37
	v_fmac_f32_e32 v66, v138, v38
	v_fmac_f32_e32 v67, v139, v39
	ds_read_b128 v[136:139], v105 offset:51520
	s_waitcnt lgkmcnt(11)
	v_fmac_f32_e32 v66, v140, v40
	v_fmac_f32_e32 v67, v141, v41
	v_fmac_f32_e32 v66, v142, v42
	v_fmac_f32_e32 v67, v143, v43
	ds_read_b128 v[140:143], v105 offset:51536
	s_waitcnt lgkmcnt(11)
	v_fmac_f32_e32 v66, v144, v44
	v_fmac_f32_e32 v67, v145, v45
	v_fmac_f32_e32 v66, v146, v46
	v_fmac_f32_e32 v67, v147, v47
	ds_read_b128 v[144:147], v105 offset:51552
	s_waitcnt lgkmcnt(11)
	v_fmac_f32_e32 v66, v148, v48
	v_fmac_f32_e32 v67, v149, v49
	v_fmac_f32_e32 v66, v150, v50
	v_fmac_f32_e32 v67, v151, v51
	ds_read_b128 v[148:151], v105 offset:51568
	s_waitcnt lgkmcnt(11)
	v_fmac_f32_e32 v66, v152, v52
	v_fmac_f32_e32 v67, v153, v53
	v_fmac_f32_e32 v66, v154, v54
	v_fmac_f32_e32 v67, v155, v55
	ds_read_b128 v[152:155], v105 offset:51584
	s_waitcnt lgkmcnt(11)
	v_fmac_f32_e32 v66, v156, v56
	v_fmac_f32_e32 v67, v157, v57
	v_fmac_f32_e32 v66, v158, v58
	v_fmac_f32_e32 v67, v159, v59
	ds_read_b128 v[156:159], v105 offset:51600
	s_waitcnt lgkmcnt(11)
	v_fmac_f32_e32 v66, v160, v60
	v_fmac_f32_e32 v67, v161, v61
	v_fmac_f32_e32 v66, v162, v62
	v_fmac_f32_e32 v67, v163, v63
	ds_read_b128 v[160:163], v105 offset:51616
	s_waitcnt lgkmcnt(11)
	v_fmac_f32_e32 v66, v164, v64
	v_fmac_f32_e32 v67, v165, v65
	v_sub_f32_e32 v2, v2, v66
	v_sub_f32_e32 v2, v2, v67
	ds_read_b128 v[164:167], v105 offset:51632
	s_waitcnt lgkmcnt(11)
	v_mul_f32_e32 v66, v168, v0
	v_mul_f32_e32 v67, v169, v4
	v_fmac_f32_e32 v66, v170, v5
	v_fmac_f32_e32 v67, v171, v6
	ds_read_b128 v[168:171], v105 offset:51648
	s_waitcnt lgkmcnt(11)
	v_fmac_f32_e32 v66, v172, v7
	v_fmac_f32_e32 v67, v173, v8
	v_fmac_f32_e32 v66, v174, v9
	v_fmac_f32_e32 v67, v175, v10
	ds_read_b128 v[172:175], v105 offset:51664
	s_waitcnt lgkmcnt(11)
	v_fmac_f32_e32 v66, v176, v11
	v_fmac_f32_e32 v67, v177, v12
	v_fmac_f32_e32 v66, v178, v13
	v_fmac_f32_e32 v67, v179, v14
	ds_read_b128 v[176:179], v105 offset:51680
	s_waitcnt lgkmcnt(11)
	v_fmac_f32_e32 v66, v180, v15
	v_fmac_f32_e32 v67, v181, v16
	v_fmac_f32_e32 v66, v182, v17
	v_fmac_f32_e32 v67, v183, v18
	ds_read_b128 v[180:183], v105 offset:51696
	s_waitcnt lgkmcnt(11)
	v_fmac_f32_e32 v66, v136, v20
	v_fmac_f32_e32 v67, v137, v21
	v_fmac_f32_e32 v66, v138, v22
	v_fmac_f32_e32 v67, v139, v23
	s_waitcnt lgkmcnt(10)
	v_fmac_f32_e32 v66, v140, v24
	v_fmac_f32_e32 v67, v141, v25
	v_fmac_f32_e32 v66, v142, v26
	v_fmac_f32_e32 v67, v143, v27
	s_waitcnt lgkmcnt(9)
	v_fmac_f32_e32 v66, v144, v28
	v_fmac_f32_e32 v67, v145, v29
	v_fmac_f32_e32 v66, v146, v30
	v_fmac_f32_e32 v67, v147, v31
	s_waitcnt lgkmcnt(8)
	v_fmac_f32_e32 v66, v148, v32
	v_fmac_f32_e32 v67, v149, v33
	v_fmac_f32_e32 v66, v150, v34
	v_fmac_f32_e32 v67, v151, v35
	s_waitcnt lgkmcnt(7)
	v_fmac_f32_e32 v66, v152, v36
	v_fmac_f32_e32 v67, v153, v37
	v_fmac_f32_e32 v66, v154, v38
	v_fmac_f32_e32 v67, v155, v39
	s_waitcnt lgkmcnt(6)
	v_fmac_f32_e32 v66, v156, v40
	v_fmac_f32_e32 v67, v157, v41
	v_fmac_f32_e32 v66, v158, v42
	v_fmac_f32_e32 v67, v159, v43
	s_waitcnt lgkmcnt(5)
	v_fmac_f32_e32 v66, v160, v44
	v_fmac_f32_e32 v67, v161, v45
	v_fmac_f32_e32 v66, v162, v46
	v_fmac_f32_e32 v67, v163, v47
	s_waitcnt lgkmcnt(4)
	v_fmac_f32_e32 v66, v164, v48
	v_fmac_f32_e32 v67, v165, v49
	v_fmac_f32_e32 v66, v166, v50
	v_fmac_f32_e32 v67, v167, v51
	s_waitcnt lgkmcnt(3)
	v_fmac_f32_e32 v66, v168, v52
	v_fmac_f32_e32 v67, v169, v53
	v_fmac_f32_e32 v66, v170, v54
	v_fmac_f32_e32 v67, v171, v55
	s_waitcnt lgkmcnt(2)
	v_fmac_f32_e32 v66, v172, v56
	v_fmac_f32_e32 v67, v173, v57
	v_fmac_f32_e32 v66, v174, v58
	v_fmac_f32_e32 v67, v175, v59
	s_waitcnt lgkmcnt(1)
	v_fmac_f32_e32 v66, v176, v60
	v_fmac_f32_e32 v67, v177, v61
	v_fmac_f32_e32 v66, v178, v62
	v_fmac_f32_e32 v67, v179, v63
	s_waitcnt lgkmcnt(0)
	v_fmac_f32_e32 v66, v180, v64
	v_fmac_f32_e32 v67, v181, v65
	v_fmac_f32_e32 v66, v182, v2
	v_sub_f32_e32 v3, v3, v66
	v_sub_f32_e32 v3, v3, v67
	s_movk_i32 s4, 0x7f
	v_cmp_lt_i32_e32 vcc, s4, v80
	s_and_saveexec_b64 s[4:5], vcc
	s_xor_b64 s[36:37], exec, s[4:5]
	s_cbranch_execz .LBB0_936
	v_lshlrev_b32_e32 v1, 1, v80
	v_cvt_pk_bf16_f32 v66, v0, v4
	ds_write_b16 v1, v66 offset:18688
	ds_write_b16_d16_hi v1, v66 offset:18944
	v_cvt_pk_bf16_f32 v67, v5, v6
	ds_write_b16 v1, v67 offset:19200
	ds_write_b16_d16_hi v1, v67 offset:19456
	v_cvt_pk_bf16_f32 v68, v7, v8
	ds_write_b16 v1, v68 offset:19712
	ds_write_b16_d16_hi v1, v68 offset:19968
	v_cvt_pk_bf16_f32 v69, v9, v10
	ds_write_b16 v1, v69 offset:20224
	ds_write_b16_d16_hi v1, v69 offset:20480
	v_cvt_pk_bf16_f32 v66, v11, v12
	ds_write_b16 v1, v66 offset:20736
	ds_write_b16_d16_hi v1, v66 offset:20992
	v_cvt_pk_bf16_f32 v67, v13, v14
	ds_write_b16 v1, v67 offset:21248
	ds_write_b16_d16_hi v1, v67 offset:21504
	v_cvt_pk_bf16_f32 v68, v15, v16
	ds_write_b16 v1, v68 offset:21760
	ds_write_b16_d16_hi v1, v68 offset:22016
	v_cvt_pk_bf16_f32 v69, v17, v18
	ds_write_b16 v1, v69 offset:22272
	ds_write_b16_d16_hi v1, v69 offset:22528
	v_cvt_pk_bf16_f32 v66, v20, v21
	ds_write_b16 v1, v66 offset:22784
	ds_write_b16_d16_hi v1, v66 offset:23040
	v_cvt_pk_bf16_f32 v67, v22, v23
	ds_write_b16 v1, v67 offset:23296
	ds_write_b16_d16_hi v1, v67 offset:23552
	v_cvt_pk_bf16_f32 v68, v24, v25
	ds_write_b16 v1, v68 offset:23808
	ds_write_b16_d16_hi v1, v68 offset:24064
	v_cvt_pk_bf16_f32 v69, v26, v27
	ds_write_b16 v1, v69 offset:24320
	ds_write_b16_d16_hi v1, v69 offset:24576
	v_cvt_pk_bf16_f32 v66, v28, v29
	ds_write_b16 v1, v66 offset:24832
	ds_write_b16_d16_hi v1, v66 offset:25088
	v_cvt_pk_bf16_f32 v67, v30, v31
	ds_write_b16 v1, v67 offset:25344
	ds_write_b16_d16_hi v1, v67 offset:25600
	v_cvt_pk_bf16_f32 v68, v32, v33
	ds_write_b16 v1, v68 offset:25856
	ds_write_b16_d16_hi v1, v68 offset:26112
	v_cvt_pk_bf16_f32 v69, v34, v35
	ds_write_b16 v1, v69 offset:26368
	ds_write_b16_d16_hi v1, v69 offset:26624
	v_cvt_pk_bf16_f32 v66, v36, v37
	ds_write_b16 v1, v66 offset:26880
	ds_write_b16_d16_hi v1, v66 offset:27136
	v_cvt_pk_bf16_f32 v67, v38, v39
	ds_write_b16 v1, v67 offset:27392
	ds_write_b16_d16_hi v1, v67 offset:27648
	v_cvt_pk_bf16_f32 v68, v40, v41
	ds_write_b16 v1, v68 offset:27904
	ds_write_b16_d16_hi v1, v68 offset:28160
	v_cvt_pk_bf16_f32 v69, v42, v43
	ds_write_b16 v1, v69 offset:28416
	ds_write_b16_d16_hi v1, v69 offset:28672
	v_cvt_pk_bf16_f32 v66, v44, v45
	ds_write_b16 v1, v66 offset:28928
	ds_write_b16_d16_hi v1, v66 offset:29184
	v_cvt_pk_bf16_f32 v67, v46, v47
	ds_write_b16 v1, v67 offset:29440
	ds_write_b16_d16_hi v1, v67 offset:29696
	v_cvt_pk_bf16_f32 v68, v48, v49
	ds_write_b16 v1, v68 offset:29952
	ds_write_b16_d16_hi v1, v68 offset:30208
	v_cvt_pk_bf16_f32 v69, v50, v51
	ds_write_b16 v1, v69 offset:30464
	ds_write_b16_d16_hi v1, v69 offset:30720
	v_cvt_pk_bf16_f32 v66, v52, v53
	ds_write_b16 v1, v66 offset:30976
	ds_write_b16_d16_hi v1, v66 offset:31232
	v_cvt_pk_bf16_f32 v67, v54, v55
	ds_write_b16 v1, v67 offset:31488
	ds_write_b16_d16_hi v1, v67 offset:31744
	v_cvt_pk_bf16_f32 v68, v56, v57
	ds_write_b16 v1, v68 offset:32000
	ds_write_b16_d16_hi v1, v68 offset:32256
	v_cvt_pk_bf16_f32 v69, v58, v59
	ds_write_b16 v1, v69 offset:32512
	ds_write_b16_d16_hi v1, v69 offset:32768
	v_cvt_pk_bf16_f32 v66, v60, v61
	ds_write_b16 v1, v66 offset:33024
	ds_write_b16_d16_hi v1, v66 offset:33280
	v_cvt_pk_bf16_f32 v67, v62, v63
	ds_write_b16 v1, v67 offset:33536
	ds_write_b16_d16_hi v1, v67 offset:33792
	v_cvt_pk_bf16_f32 v68, v64, v65
	ds_write_b16 v1, v68 offset:34048
	ds_write_b16_d16_hi v1, v68 offset:34304
	v_cvt_pk_bf16_f32 v69, v2, v3
	ds_write_b16 v1, v69 offset:34560
	ds_write_b16_d16_hi v1, v69 offset:34816

.LBB0_1384:
	v_readlane_b32 s12, v253, 0
	s_mov_b32 s20, s12
	s_ashr_i32 s21, s20, 31
	s_lshl_b64 s[12:13], s[20:21], 20
	s_add_u32 s12, s33, s12
	s_addc_u32 s13, s37, s13
	s_cmp_gt_i32 s20, 63
	s_cbranch_scc1 .LBB0_1389
	v_mov_b32_e32 v0, v230
	s_movk_i32 s14, 0x4000
	s_nop 0
	v_cmp_gt_i32_e32 vcc, s14, v0
	s_and_saveexec_b64 s[14:15], vcc
	s_cbranch_execz .LBB0_1388
	s_lshl_b32 s19, s20, 5
	s_and_b32 s20, s19, 0xffffff00
	s_ashr_i32 s21, s20, 31
	v_lshlrev_b32_e32 v1, 2, v0
	s_mov_b64 s[22:23], 0
	v_ashrrev_i32_e32 v2, 6, v0
	v_ashrrev_i32_e32 v3, 31, v2
	v_lshlrev_b64 v[2:3], 11, v[2:3]
	v_lshl_add_u64 v[10:11], v[2:3], 0, s[20:21]
	s_movk_i32 s19, 0xfc
	v_and_or_b32 v10, v1, s19, v10
	v_lshlrev_b64 v[12:13], 2, v[10:11]
	v_lshl_add_u64 v[160:161], s[94:95], 0, v[12:13]
	v_lshl_add_u64 v[162:163], s[2:3], 0, v[12:13]
	v_lshl_add_u64 v[164:165], s[0:1], 0, v[12:13]
	v_lshl_add_u64 v[166:167], s[4:5], 0, v[12:13]
	v_lshl_add_u64 v[168:169], v[10:11], 1, s[12:13]
	s_mov_b64 s[100:101], 0x10000
	s_mov_b32 s19, 8
.Lp5prep_loop:
	global_load_dwordx4 v[172:175], v[160:161], off
	v_lshl_add_u64 v[160:161], v[160:161], 0, s[100:101]
	global_load_dwordx4 v[176:179], v[162:163], off
	v_lshl_add_u64 v[162:163], v[162:163], 0, s[100:101]
	global_load_dwordx4 v[180:183], v[164:165], off
	v_lshl_add_u64 v[164:165], v[164:165], 0, s[100:101]
	global_load_dwordx4 v[184:187], v[166:167], off
	v_lshl_add_u64 v[166:167], v[166:167], 0, s[100:101]
	global_load_dwordx4 v[188:191], v[160:161], off
	v_lshl_add_u64 v[160:161], v[160:161], 0, s[100:101]
	global_load_dwordx4 v[192:195], v[162:163], off
	v_lshl_add_u64 v[162:163], v[162:163], 0, s[100:101]
	global_load_dwordx4 v[196:199], v[164:165], off
	v_lshl_add_u64 v[164:165], v[164:165], 0, s[100:101]
	global_load_dwordx4 v[200:203], v[166:167], off
	v_lshl_add_u64 v[166:167], v[166:167], 0, s[100:101]
	global_load_dwordx4 v[204:207], v[160:161], off
	v_lshl_add_u64 v[160:161], v[160:161], 0, s[100:101]
	global_load_dwordx4 v[208:211], v[162:163], off
	v_lshl_add_u64 v[162:163], v[162:163], 0, s[100:101]
	global_load_dwordx4 v[212:215], v[164:165], off
	v_lshl_add_u64 v[164:165], v[164:165], 0, s[100:101]
	global_load_dwordx4 v[216:219], v[166:167], off
	v_lshl_add_u64 v[166:167], v[166:167], 0, s[100:101]
	global_load_dwordx4 v[220:223], v[160:161], off
	v_lshl_add_u64 v[160:161], v[160:161], 0, s[100:101]
	global_load_dwordx4 v[224:227], v[162:163], off
	v_lshl_add_u64 v[162:163], v[162:163], 0, s[100:101]
	global_load_dwordx4 v[232:235], v[164:165], off
	v_lshl_add_u64 v[164:165], v[164:165], 0, s[100:101]
	global_load_dwordx4 v[236:239], v[166:167], off
	v_lshl_add_u64 v[166:167], v[166:167], 0, s[100:101]
	s_waitcnt vmcnt(12)
	v_pk_add_f32 v[176:177], v[172:173], v[176:177]
	v_pk_add_f32 v[178:179], v[174:175], v[178:179]
	v_pk_add_f32 v[176:177], v[176:177], v[180:181]
	v_pk_add_f32 v[178:179], v[178:179], v[182:183]
	v_pk_add_f32 v[176:177], v[176:177], v[184:185]
	v_pk_add_f32 v[178:179], v[178:179], v[186:187]
	v_cvt_pk_bf16_f32 v172, v176, v177
	v_cvt_pk_bf16_f32 v173, v178, v179
	global_store_dwordx2 v[168:169], v[172:173], off
	v_add_co_u32_e32 v168, vcc, 0x8000, v168
	s_nop 1
	v_addc_co_u32_e32 v169, vcc, 0, v169, vcc
	s_waitcnt vmcnt(9)
	v_pk_add_f32 v[192:193], v[188:189], v[192:193]
	v_pk_add_f32 v[194:195], v[190:191], v[194:195]
	v_pk_add_f32 v[192:193], v[192:193], v[196:197]
	v_pk_add_f32 v[194:195], v[194:195], v[198:199]
	v_pk_add_f32 v[192:193], v[192:193], v[200:201]
	v_pk_add_f32 v[194:195], v[194:195], v[202:203]
	v_cvt_pk_bf16_f32 v188, v192, v193
	v_cvt_pk_bf16_f32 v189, v194, v195
	global_store_dwordx2 v[168:169], v[188:189], off
	v_add_co_u32_e32 v168, vcc, 0x8000, v168
	s_nop 1
	v_addc_co_u32_e32 v169, vcc, 0, v169, vcc
	s_waitcnt vmcnt(6)
	v_pk_add_f32 v[208:209], v[204:205], v[208:209]
	v_pk_add_f32 v[210:211], v[206:207], v[210:211]
	v_pk_add_f32 v[208:209], v[208:209], v[212:213]
	v_pk_add_f32 v[210:211], v[210:211], v[214:215]
	v_pk_add_f32 v[208:209], v[208:209], v[216:217]
	v_pk_add_f32 v[210:211], v[210:211], v[218:219]
	v_cvt_pk_bf16_f32 v204, v208, v209
	v_cvt_pk_bf16_f32 v205, v210, v211
	global_store_dwordx2 v[168:169], v[204:205], off
	v_add_co_u32_e32 v168, vcc, 0x8000, v168
	s_nop 1
	v_addc_co_u32_e32 v169, vcc, 0, v169, vcc
	s_waitcnt vmcnt(3)
	v_pk_add_f32 v[224:225], v[220:221], v[224:225]
	v_pk_add_f32 v[226:227], v[222:223], v[226:227]
	v_pk_add_f32 v[224:225], v[224:225], v[232:233]
	v_pk_add_f32 v[226:227], v[226:227], v[234:235]
	v_pk_add_f32 v[224:225], v[224:225], v[236:237]
	v_pk_add_f32 v[226:227], v[226:227], v[238:239]
	v_cvt_pk_bf16_f32 v220, v224, v225
	v_cvt_pk_bf16_f32 v221, v226, v227
	global_store_dwordx2 v[168:169], v[220:221], off
	v_add_co_u32_e32 v168, vcc, 0x8000, v168
	s_nop 1
	v_addc_co_u32_e32 v169, vcc, 0, v169, vcc
	s_sub_u32 s19, s19, 1
	s_cmp_lg_u32 s19, 0
	s_cbranch_scc1 .Lp5prep_loop
